# pool items: slow sample-row pool items on 4 dedicated workgroups; pool_fill guarded head-row loads issued together with one wait
# baseline (speedup 1.0000x reference)
; __global__ void __launch_bounds__(512) mk_fwd(Args a) {
;     ...
;             if ((int)blockIdx.x >= 32 || G <= 32) {
;                 const int nb = (G > 32) ? G - 32 : G, b0 = (G > 32) ? (int)blockIdx.x - 32 : (int)blockIdx.x;
;                 for (int it = b0; it < 512 + 516; it += nb) {
;                     if (PHON(6) && it < 512) sample_item(lds, a, l, it);
;                     else if (PHON(7) && it >= 512) pool_item(lds, a, l, it - 512);
;                 }
;             }
.LBB0_114:
	v_readlane_b32 s8, v254, 33
	v_readlane_b32 s9, v254, 34
	s_andn2_b64 vcc, exec, s[8:9]
	s_cbranch_vccnz .LBB0_218
	v_readlane_b32 s2, v255, 5
	s_add_u32 s2, s2, 0x2800000
	v_readlane_b32 s8, v255, 6
	s_addc_u32 s28, s8, 0
	s_lshl_b32 s29, s25, 7
	s_lshl_b32 s10, s25, 9
	s_add_i32 s34, s29, 0xffffc000
	s_ashr_i32 s11, s10, 31
	v_readlane_b32 s35, v254, 9
	v_readlane_b32 s8, v254, 8
	s_add_i32 s8, s8, -4
	s_cmp_ge_i32 s35, s8
	s_cbranch_scc0 .Litems_regular
	s_sub_i32 s35, s35, s8
	s_addk_i32 s35, 0x400
.Litems_regular:
	s_branch .LBB0_118
.LBB0_116:
	s_or_b64 exec, exec, s[12:13]
	s_barrier
.LBB0_117:
	v_readlane_b32 s8, v254, 8
	s_add_i32 s8, s8, -4
	s_add_i32 s35, s35, s8
	s_cmpk_gt_i32 s35, 0x3ff
	s_waitcnt vmcnt(63) expcnt(7) lgkmcnt(15)
	s_cbranch_scc1 .LBB0_218

; DI float bflo(unsigned w) { return __uint_as_float(w << 16); }
; DI float bfhi(unsigned w) { return __uint_as_float(w & 0xffff0000u); }
; template <int W>
; DI void pool_fill(LAS bf16_t* dA, const Args& a, int l, int g, int t0, int tid) {
;     ...
;         const int tpos0 = row0 & 2047;
;         const bf16_t* pp = PROJ + (size_t)row0 * NPROJ + 2048 + g * 128 + c0;
;         f32x4 pv[W + 7];
; #pragma unroll
;         for (int i = 0; i < W + 7; ++i) { const int dr = i - (W - 1);
;             if (tpos0 + dr >= 0) { const u32x2 rw = *(const u32x2*)(pp + (long)dr * NPROJ); pv[i] = (f32x4){bflo(rw.x), bfhi(rw.x), bflo(rw.y), bfhi(rw.y)}; }
;             else pv[i] = (f32x4){0.f, 0.f, 0.f, 0.f}; }
.LBB0_126:
	s_andn2_b64 vcc, exec, s[8:9]
	s_cbranch_vccnz .LBB0_158
	v_mov_b64_e32 v[0:1], s[72:73]
	v_mad_i64_i32 v[0:1], s[8:9], v91, s42, v[0:1]
	v_lshlrev_b32_e32 v128, 1, v90
	v_and_b32_e32 v93, 0x7f8, v91
	v_lshl_add_u64 v[0:1], v[0:1], 0, v[128:129]
	s_mov_b64 s[8:9], 0x1300
	v_lshl_add_u64 v[58:59], v[0:1], 0, s[8:9]
	v_cmp_lt_u32_e32 vcc, 14, v93
	v_mov_b32_e32 v34, 0
	v_mov_b32_e32 v60, 0
	v_mov_b32_e32 v61, 0
	v_mov_b32_e32 v56, 0
	v_mov_b32_e32 v57, 0
	v_mov_b32_e32 v102, 0
	v_mov_b32_e32 v103, 0
	s_and_saveexec_b64 s[8:9], vcc
	s_cbranch_execz .LBB0_129
	v_add_co_u32_e32 v0, vcc, 0xfffee000, v58
	s_nop 1
	v_addc_co_u32_e32 v1, vcc, -1, v59, vcc
	global_load_dwordx2 v[102:103], v[0:1], off offset:-3072
.LBB0_129:
	s_or_b64 exec, exec, s[8:9]
	v_cmp_lt_u32_e32 vcc, 13, v93
	v_mov_b32_e32 v35, 0
	v_mov_b32_e32 v44, 0
	v_mov_b32_e32 v45, 0
	v_mov_b32_e32 v104, 0
	v_mov_b32_e32 v105, 0
	s_and_saveexec_b64 s[8:9], vcc
	s_cbranch_execz .LBB0_131
	v_add_co_u32_e32 v0, vcc, 0xfffef000, v58
	s_nop 1
	v_addc_co_u32_e32 v1, vcc, -1, v59, vcc
	global_load_dwordx2 v[104:105], v[0:1], off offset:-2048
.LBB0_131:
	s_or_b64 exec, exec, s[8:9]
	v_cmp_lt_u32_e32 vcc, 12, v93
	v_mov_b32_e32 v18, 0
	v_mov_b32_e32 v36, 0
	v_mov_b32_e32 v37, 0
	v_mov_b32_e32 v38, 0
	v_mov_b32_e32 v39, 0
	v_mov_b32_e32 v106, 0
	v_mov_b32_e32 v107, 0
	s_and_saveexec_b64 s[8:9], vcc
	s_cbranch_execz .LBB0_133
	v_add_co_u32_e32 v0, vcc, 0xffff0000, v58
	s_nop 1
	v_addc_co_u32_e32 v1, vcc, -1, v59, vcc
	global_load_dwordx2 v[106:107], v[0:1], off offset:-1024
.LBB0_133:
	s_or_b64 exec, exec, s[8:9]
	v_cmp_lt_u32_e32 vcc, 11, v93
	v_mov_b32_e32 v19, 0
	v_mov_b32_e32 v32, 0
	v_mov_b32_e32 v33, 0
	v_mov_b32_e32 v108, 0
	v_mov_b32_e32 v109, 0
	s_and_saveexec_b64 s[8:9], vcc
	s_cbranch_execz .LBB0_135
	v_add_co_u32_e32 v0, vcc, 0xffff1000, v58
	s_nop 1
	v_addc_co_u32_e32 v1, vcc, -1, v59, vcc
	global_load_dwordx2 v[108:109], v[0:1], off
.LBB0_135:
	s_or_b64 exec, exec, s[8:9]
	v_cmp_lt_u32_e32 vcc, 10, v93
	v_mov_b32_e32 v4, 0
	v_mov_b32_e32 v22, 0
	v_mov_b32_e32 v23, 0
	v_mov_b32_e32 v24, 0
	v_mov_b32_e32 v25, 0
	v_mov_b32_e32 v110, 0
	v_mov_b32_e32 v111, 0
	s_and_saveexec_b64 s[8:9], vcc
	s_cbranch_execz .LBB0_137
	v_add_co_u32_e32 v0, vcc, 0xffff3000, v58
	s_nop 1
	v_addc_co_u32_e32 v1, vcc, -1, v59, vcc
	global_load_dwordx2 v[110:111], v[0:1], off offset:-3072
.LBB0_137:
	s_or_b64 exec, exec, s[8:9]
	v_cmp_lt_u32_e32 vcc, 9, v93
	v_mov_b32_e32 v5, 0
	v_mov_b32_e32 v16, 0
	v_mov_b32_e32 v17, 0
	v_mov_b32_e32 v112, 0
	v_mov_b32_e32 v113, 0
	s_and_saveexec_b64 s[8:9], vcc
	s_cbranch_execz .LBB0_139
	v_add_co_u32_e32 v0, vcc, 0xffff4000, v58
	s_nop 1
	v_addc_co_u32_e32 v1, vcc, -1, v59, vcc
	global_load_dwordx2 v[112:113], v[0:1], off offset:-2048
.LBB0_139:
	s_or_b64 exec, exec, s[8:9]
	v_cmp_lt_u32_e32 vcc, 8, v93
	v_mov_b32_e32 v0, 0
	v_mov_b32_e32 v6, 0
	v_mov_b32_e32 v7, 0
	v_mov_b32_e32 v10, 0
	v_mov_b32_e32 v11, 0
	v_mov_b32_e32 v114, 0
	v_mov_b32_e32 v115, 0
	s_and_saveexec_b64 s[8:9], vcc
	s_cbranch_execz .LBB0_141
	v_add_co_u32_e32 v2, vcc, 0xffff5000, v58
	s_nop 1
	v_addc_co_u32_e32 v3, vcc, -1, v59, vcc
	global_load_dwordx2 v[114:115], v[2:3], off offset:-1024
.LBB0_141:
	s_or_b64 exec, exec, s[8:9]
	v_cmp_ne_u32_e64 s[8:9], 0, v93
	v_mov_b32_e32 v1, 0
	v_mov_b32_e32 v2, 0
	v_mov_b32_e32 v3, 0
	v_mov_b32_e32 v116, 0
	v_mov_b32_e32 v117, 0
	s_and_saveexec_b64 s[14:15], s[8:9]
	s_cbranch_execz .LBB0_143
	v_add_co_u32_e32 v0, vcc, 0xffff6000, v58
	s_nop 1
	v_addc_co_u32_e32 v1, vcc, -1, v59, vcc
	global_load_dwordx2 v[116:117], v[0:1], off
.LBB0_143:
	s_or_b64 exec, exec, s[14:15]
	v_mov_b32_e32 v8, 0
	v_mov_b32_e32 v12, 0
	v_mov_b32_e32 v13, 0
	v_mov_b32_e32 v14, 0
	v_mov_b32_e32 v15, 0
	v_mov_b32_e32 v118, 0
	v_mov_b32_e32 v119, 0
	s_and_saveexec_b64 s[14:15], s[8:9]
	s_cbranch_execz .LBB0_145
	v_add_co_u32_e32 v12, vcc, 0xffff8000, v58
	s_nop 1
	v_addc_co_u32_e32 v13, vcc, -1, v59, vcc
	global_load_dwordx2 v[118:119], v[12:13], off offset:-3072
.LBB0_145:
	s_or_b64 exec, exec, s[14:15]
	v_mov_b32_e32 v9, 0
	v_mov_b32_e32 v20, 0
	v_mov_b32_e32 v21, 0
	v_mov_b32_e32 v120, 0
	v_mov_b32_e32 v121, 0
	s_and_saveexec_b64 s[14:15], s[8:9]
	s_cbranch_execz .LBB0_147
	v_add_co_u32_e32 v8, vcc, 0xffff9000, v58
	s_nop 1
	v_addc_co_u32_e32 v9, vcc, -1, v59, vcc
	global_load_dwordx2 v[120:121], v[8:9], off offset:-2048
.LBB0_147:
	s_or_b64 exec, exec, s[14:15]
	v_mov_b32_e32 v26, 0
	v_mov_b32_e32 v28, 0
	v_mov_b32_e32 v29, 0
	v_mov_b32_e32 v30, 0
	v_mov_b32_e32 v31, 0
	v_mov_b32_e32 v122, 0
	v_mov_b32_e32 v123, 0
	s_and_saveexec_b64 s[14:15], s[8:9]
	s_cbranch_execz .LBB0_149
	v_add_co_u32_e32 v28, vcc, 0xffffa000, v58
	s_nop 1
	v_addc_co_u32_e32 v29, vcc, -1, v59, vcc
	global_load_dwordx2 v[122:123], v[28:29], off offset:-1024
.LBB0_149:
	s_or_b64 exec, exec, s[14:15]
	v_mov_b32_e32 v27, 0
	v_mov_b32_e32 v40, 0
	v_mov_b32_e32 v41, 0
	v_mov_b32_e32 v124, 0
	v_mov_b32_e32 v125, 0
	s_and_saveexec_b64 s[14:15], s[8:9]
	s_cbranch_execz .LBB0_151
	v_add_co_u32_e32 v26, vcc, 0xffffb000, v58
	s_nop 1
	v_addc_co_u32_e32 v27, vcc, -1, v59, vcc
	global_load_dwordx2 v[124:125], v[26:27], off
.LBB0_151:
	s_or_b64 exec, exec, s[14:15]
	v_mov_b32_e32 v42, 0
	v_mov_b32_e32 v46, 0
	v_mov_b32_e32 v47, 0
	v_mov_b32_e32 v48, 0
	v_mov_b32_e32 v49, 0
	v_mov_b32_e32 v126, 0
	v_mov_b32_e32 v127, 0
	s_and_saveexec_b64 s[14:15], s[8:9]
	s_cbranch_execz .LBB0_153
	v_add_co_u32_e32 v46, vcc, 0xffffd000, v58
	s_nop 1
	v_addc_co_u32_e32 v47, vcc, -1, v59, vcc
	global_load_dwordx2 v[126:127], v[46:47], off offset:-3072
; #define LAS __attribute__((address_space(3)))
; DI unsigned pk2(float a, float b) { f32x2 v = {a, b}; nbf2 r = __builtin_convertvector(v, nbf2); return __builtin_bit_cast(unsigned, r); }
; DI float bflo(unsigned w) { return __uint_as_float(w << 16); }
; DI float bfhi(unsigned w) { return __uint_as_float(w & 0xffff0000u); }
; template <int W>
; DI void pool_fill(LAS bf16_t* dA, const Args& a, int l, int g, int t0, int tid) {
;     ...
;         f32x4 pv[W + 7];
; #pragma unroll
;         for (int i = 0; i < W + 7; ++i) { const int dr = i - (W - 1);
;             if (tpos0 + dr >= 0) { const u32x2 rw = *(const u32x2*)(pp + (long)dr * NPROJ); pv[i] = (f32x4){bflo(rw.x), bfhi(rw.x), bflo(rw.y), bfhi(rw.y)}; }
;             else pv[i] = (f32x4){0.f, 0.f, 0.f, 0.f}; }
; #pragma unroll
;         for (int j = 0; j < 8; ++j) { f32x4 sum = pv[j];
; #pragma unroll
;             for (int i = 1; i < W; ++i) sum += pv[j + i];
;             const int tp = tpos0 + j; const float inv = __builtin_amdgcn_rcpf((float)((tp + 1 < W) ? tp + 1 : W));
;             const f32x4 d = sum * inv - pv[j + W - 1]; u32x2 pw; pw.x = pk2(d[0], d[1]); pw.y = pk2(d[2], d[3]); *(LAS u32x2*)(dA + (lr0 + j) * 136 + c0) = pw; }
.LBB0_153:
	s_or_b64 exec, exec, s[14:15]
	v_mov_b32_e32 v43, 0
	v_mov_b32_e32 v50, 0
	v_mov_b32_e32 v51, 0
	v_mov_b32_e32 v132, 0
	v_mov_b32_e32 v133, 0
	s_and_saveexec_b64 s[14:15], s[8:9]
	s_cbranch_execz .LBB0_155
	v_add_co_u32_e32 v42, vcc, 0xffffe000, v58
	s_nop 1
	v_addc_co_u32_e32 v43, vcc, -1, v59, vcc
	global_load_dwordx2 v[132:133], v[42:43], off offset:-2048
.LBB0_155:
	s_or_b64 exec, exec, s[14:15]
	v_mov_b32_e32 v52, 0
	v_mov_b32_e32 v53, 0
	v_mov_b32_e32 v54, 0
	v_mov_b32_e32 v55, 0
	v_mov_b32_e32 v134, 0
	v_mov_b32_e32 v135, 0
	s_and_saveexec_b64 s[14:15], s[8:9]
	s_cbranch_execz .LBB0_157
	v_add_co_u32_e32 v52, vcc, 0xfffff000, v58
	s_nop 1
	v_addc_co_u32_e32 v53, vcc, -1, v59, vcc
	global_load_dwordx2 v[134:135], v[52:53], off offset:-1024
.LBB0_157:
	s_or_b64 exec, exec, s[14:15]
	s_waitcnt vmcnt(0)
	v_lshlrev_b32_e32 v60, 16, v102
	v_and_b32_e32 v61, 0xffff0000, v102
	v_lshlrev_b32_e32 v56, 16, v103
	v_and_b32_e32 v57, 0xffff0000, v103
	v_lshlrev_b32_e32 v34, 16, v104
	v_and_b32_e32 v35, 0xffff0000, v104
	v_lshlrev_b32_e32 v44, 16, v105
	v_and_b32_e32 v45, 0xffff0000, v105
	v_lshlrev_b32_e32 v36, 16, v106
	v_and_b32_e32 v37, 0xffff0000, v106
	v_lshlrev_b32_e32 v38, 16, v107
	v_and_b32_e32 v39, 0xffff0000, v107
	v_lshlrev_b32_e32 v18, 16, v108
	v_and_b32_e32 v19, 0xffff0000, v108
	v_lshlrev_b32_e32 v32, 16, v109
	v_and_b32_e32 v33, 0xffff0000, v109
	v_lshlrev_b32_e32 v22, 16, v110
	v_and_b32_e32 v23, 0xffff0000, v110
	v_lshlrev_b32_e32 v24, 16, v111
	v_and_b32_e32 v25, 0xffff0000, v111
	v_lshlrev_b32_e32 v4, 16, v112
	v_and_b32_e32 v5, 0xffff0000, v112
	v_lshlrev_b32_e32 v16, 16, v113
	v_and_b32_e32 v17, 0xffff0000, v113
	v_lshlrev_b32_e32 v6, 16, v114
	v_and_b32_e32 v7, 0xffff0000, v114
	v_lshlrev_b32_e32 v10, 16, v115
	v_and_b32_e32 v11, 0xffff0000, v115
	v_lshlrev_b32_e32 v0, 16, v116
	v_and_b32_e32 v1, 0xffff0000, v116
	v_lshlrev_b32_e32 v2, 16, v117
	v_and_b32_e32 v3, 0xffff0000, v117
	v_lshlrev_b32_e32 v12, 16, v118
	v_and_b32_e32 v13, 0xffff0000, v118
	v_lshlrev_b32_e32 v14, 16, v119
	v_and_b32_e32 v15, 0xffff0000, v119
	v_lshlrev_b32_e32 v8, 16, v120
	v_and_b32_e32 v9, 0xffff0000, v120
	v_lshlrev_b32_e32 v20, 16, v121
	v_and_b32_e32 v21, 0xffff0000, v121
	v_lshlrev_b32_e32 v28, 16, v122
	v_and_b32_e32 v29, 0xffff0000, v122
	v_lshlrev_b32_e32 v30, 16, v123
	v_and_b32_e32 v31, 0xffff0000, v123
	v_lshlrev_b32_e32 v26, 16, v124
	v_and_b32_e32 v27, 0xffff0000, v124
	v_lshlrev_b32_e32 v40, 16, v125
	v_and_b32_e32 v41, 0xffff0000, v125
	v_lshlrev_b32_e32 v46, 16, v126
	v_and_b32_e32 v47, 0xffff0000, v126
	v_lshlrev_b32_e32 v48, 16, v127
	v_and_b32_e32 v49, 0xffff0000, v127
	v_lshlrev_b32_e32 v42, 16, v132
	v_and_b32_e32 v43, 0xffff0000, v132
	v_lshlrev_b32_e32 v50, 16, v133
	v_and_b32_e32 v51, 0xffff0000, v133
	v_lshlrev_b32_e32 v52, 16, v134
	v_and_b32_e32 v53, 0xffff0000, v134
	v_lshlrev_b32_e32 v54, 16, v135
	v_and_b32_e32 v55, 0xffff0000, v135
	v_add_co_u32_e32 v62, vcc, 0x1000, v58
	s_movk_i32 s8, 0x5000
	s_nop 0
	v_addc_co_u32_e32 v63, vcc, 0, v59, vcc
	global_load_dwordx2 v[64:65], v[58:59], off
	global_load_dwordx2 v[78:79], v[62:63], off offset:1024
	v_add_co_u32_e32 v62, vcc, s8, v58
	s_movk_i32 s8, 0x6000
	s_nop 0
	v_addc_co_u32_e32 v63, vcc, 0, v59, vcc
	v_add_co_u32_e32 v66, vcc, s8, v58
	s_movk_i32 s8, 0x7000
	s_nop 0
	v_addc_co_u32_e32 v67, vcc, 0, v59, vcc
	v_add_co_u32_e32 v68, vcc, s8, v58
	global_load_dwordx2 v[62:63], v[62:63], off
	s_nop 0
	v_addc_co_u32_e32 v69, vcc, 0, v59, vcc
	global_load_dwordx2 v[66:67], v[66:67], off offset:1024
	s_movk_i32 s8, 0x3000
	global_load_dwordx2 v[72:73], v[68:69], off offset:2048
	v_add_co_u32_e32 v68, vcc, s49, v58
	v_pk_add_f32 v[56:57], v[56:57], v[44:45]
	s_nop 0
	v_addc_co_u32_e32 v69, vcc, 0, v59, vcc
	global_load_dwordx2 v[76:77], v[68:69], off offset:3072
	v_add_co_u32_e32 v68, vcc, s93, v58
	v_pk_add_f32 v[56:57], v[56:57], v[38:39]
	s_nop 0
	v_addc_co_u32_e32 v69, vcc, 0, v59, vcc
	global_load_dwordx2 v[82:83], v[68:69], off offset:2048
	v_add_co_u32_e32 v58, vcc, s8, v58
	v_pk_add_f32 v[56:57], v[56:57], v[32:33]
	s_nop 0
	v_addc_co_u32_e32 v59, vcc, 0, v59, vcc
	global_load_dwordx2 v[86:87], v[58:59], off offset:3072
	v_pk_add_f32 v[58:59], v[60:61], v[34:35]
	v_pk_add_f32 v[56:57], v[56:57], v[24:25]
	v_pk_add_f32 v[58:59], v[58:59], v[36:37]
	v_pk_add_f32 v[56:57], v[56:57], v[16:17]
	v_pk_add_f32 v[58:59], v[58:59], v[18:19]
	v_pk_add_f32 v[56:57], v[56:57], v[10:11]
	v_pk_add_f32 v[58:59], v[58:59], v[22:23]
	v_pk_add_f32 v[96:97], v[56:57], v[2:3]
	v_pk_add_f32 v[58:59], v[58:59], v[4:5]
	v_pk_add_f32 v[96:97], v[96:97], v[14:15]
	v_pk_add_f32 v[58:59], v[58:59], v[6:7]
	v_pk_add_f32 v[96:97], v[96:97], v[20:21]
	v_pk_add_f32 v[94:95], v[58:59], v[0:1]
	v_min_u32_e32 v98, 15, v93
	v_pk_add_f32 v[94:95], v[94:95], v[12:13]
	v_pk_add_f32 v[96:97], v[96:97], v[30:31]
	v_pk_add_f32 v[94:95], v[94:95], v[8:9]
	v_add_u32_e32 v98, 1, v98
	v_pk_add_f32 v[94:95], v[94:95], v[28:29]
	v_pk_add_f32 v[96:97], v[96:97], v[40:41]
	v_cvt_f32_ubyte0_e32 v98, v98
	v_pk_add_f32 v[44:45], v[44:45], v[38:39]
	v_pk_add_f32 v[94:95], v[94:95], v[26:27]
	v_pk_add_f32 v[96:97], v[96:97], v[48:49]
	v_rcp_iflag_f32_e32 v98, v98
	v_pk_add_f32 v[34:35], v[34:35], v[36:37]
	v_pk_add_f32 v[44:45], v[44:45], v[32:33]
	v_pk_add_f32 v[94:95], v[94:95], v[46:47]
	v_pk_add_f32 v[96:97], v[96:97], v[50:51]
	v_pk_add_f32 v[34:35], v[34:35], v[18:19]
	v_pk_add_f32 v[44:45], v[44:45], v[24:25]
	v_pk_add_f32 v[94:95], v[94:95], v[42:43]
	v_pk_add_f32 v[96:97], v[96:97], v[54:55]
	v_pk_add_f32 v[34:35], v[34:35], v[22:23]
	v_pk_add_f32 v[44:45], v[44:45], v[16:17]
	v_pk_add_f32 v[94:95], v[94:95], v[52:53]
	v_pk_add_f32 v[34:35], v[34:35], v[4:5]
	v_pk_add_f32 v[44:45], v[44:45], v[10:11]
	v_pk_add_f32 v[34:35], v[34:35], v[6:7]
	v_pk_add_f32 v[44:45], v[44:45], v[2:3]
	v_pk_add_f32 v[34:35], v[34:35], v[0:1]
	v_pk_add_f32 v[44:45], v[44:45], v[14:15]
	s_waitcnt vmcnt(7)
; #define LAS __attribute__((address_space(3)))
; DI unsigned pk2(float a, float b) { f32x2 v = {a, b}; nbf2 r = __builtin_convertvector(v, nbf2); return __builtin_bit_cast(unsigned, r); }
; template <int W>
; DI void pool_fill(LAS bf16_t* dA, const Args& a, int l, int g, int t0, int tid) {
;     ...
;         for (int j = 0; j < 8; ++j) { f32x4 sum = pv[j];
; #pragma unroll
;             for (int i = 1; i < W; ++i) sum += pv[j + i];
;             const int tp = tpos0 + j; const float inv = __builtin_amdgcn_rcpf((float)((tp + 1 < W) ? tp + 1 : W));
;             const f32x4 d = sum * inv - pv[j + W - 1]; u32x2 pw; pw.x = pk2(d[0], d[1]); pw.y = pk2(d[2], d[3]); *(LAS u32x2*)(dA + (lr0 + j) * 136 + c0) = pw; }
	v_lshlrev_b32_e32 v74, 16, v65
	v_and_b32_e32 v75, 0xffff0000, v65
	v_lshlrev_b32_e32 v70, 16, v64
	v_and_b32_e32 v71, 0xffff0000, v64
	v_pk_add_f32 v[96:97], v[96:97], v[74:75]
	v_xor_b32_e32 v101, 0x80000000, v75
	v_xor_b32_e32 v100, 0x80000000, v74
	v_pk_add_f32 v[94:95], v[94:95], v[70:71]
	v_pk_fma_f32 v[96:97], v[98:99], v[96:97], v[100:101] op_sel_hi:[0,1,1]
	v_xor_b32_e32 v101, 0x80000000, v71
	v_xor_b32_e32 v100, 0x80000000, v70
	v_pk_fma_f32 v[94:95], v[98:99], v[94:95], v[100:101] op_sel_hi:[0,1,1]
	v_cvt_pk_bf16_f32 v94, v94, v95
	v_cvt_pk_bf16_f32 v95, v96, v97
	v_mul_lo_u32 v96, v92, s47
	v_pk_add_f32 v[34:35], v[34:35], v[12:13]
	v_pk_add_f32 v[44:45], v[44:45], v[20:21]
	v_add3_u32 v97, 0, v128, v96
	v_pk_add_f32 v[34:35], v[34:35], v[8:9]
	v_pk_add_f32 v[44:45], v[44:45], v[30:31]
	v_min_u32_e32 v96, 14, v93
	v_pk_add_f32 v[34:35], v[34:35], v[28:29]
	v_pk_add_f32 v[44:45], v[44:45], v[40:41]
	v_add_u32_e32 v96, 2, v96
	v_pk_add_f32 v[34:35], v[34:35], v[26:27]
	v_pk_add_f32 v[44:45], v[44:45], v[48:49]
	v_cvt_f32_ubyte0_e32 v96, v96
	v_pk_add_f32 v[34:35], v[34:35], v[46:47]
	v_pk_add_f32 v[44:45], v[44:45], v[50:51]
	v_rcp_iflag_f32_e32 v96, v96
	v_pk_add_f32 v[34:35], v[34:35], v[42:43]
	v_pk_add_f32 v[44:45], v[44:45], v[54:55]
	s_waitcnt vmcnt(6)
	v_lshlrev_b32_e32 v80, 16, v79
	v_and_b32_e32 v81, 0xffff0000, v79
	v_pk_add_f32 v[34:35], v[34:35], v[52:53]
	v_pk_add_f32 v[44:45], v[44:45], v[74:75]
	s_waitcnt vmcnt(2)
	v_lshlrev_b32_e32 v56, 16, v76
	v_and_b32_e32 v57, 0xffff0000, v76
	v_lshlrev_b32_e32 v58, 16, v77
	v_and_b32_e32 v59, 0xffff0000, v77
	v_lshlrev_b32_e32 v76, 16, v78
	v_and_b32_e32 v77, 0xffff0000, v78
	v_pk_add_f32 v[34:35], v[34:35], v[70:71]
	v_pk_add_f32 v[44:45], v[44:45], v[80:81]
	v_xor_b32_e32 v99, 0x80000000, v81
	v_xor_b32_e32 v98, 0x80000000, v80
	v_pk_add_f32 v[34:35], v[34:35], v[76:77]
	v_pk_fma_f32 v[44:45], v[96:97], v[44:45], v[98:99] op_sel_hi:[0,1,1]
	v_xor_b32_e32 v99, 0x80000000, v77
	v_xor_b32_e32 v98, 0x80000000, v76
	v_pk_fma_f32 v[34:35], v[96:97], v[34:35], v[98:99] op_sel_hi:[0,1,1]
	v_cvt_pk_bf16_f32 v34, v34, v35
	v_cvt_pk_bf16_f32 v35, v44, v45
	ds_write2_b64 v97, v[94:95], v[34:35] offset1:34
	v_pk_add_f32 v[34:35], v[36:37], v[18:19]
	v_pk_add_f32 v[36:37], v[38:39], v[32:33]
	v_pk_add_f32 v[34:35], v[34:35], v[22:23]
	v_pk_add_f32 v[36:37], v[36:37], v[24:25]
	v_pk_add_f32 v[34:35], v[34:35], v[4:5]
	v_pk_add_f32 v[36:37], v[36:37], v[16:17]
	v_pk_add_f32 v[34:35], v[34:35], v[6:7]
	v_pk_add_f32 v[36:37], v[36:37], v[10:11]
	v_pk_add_f32 v[34:35], v[34:35], v[0:1]
	v_pk_add_f32 v[36:37], v[36:37], v[2:3]
	v_pk_add_f32 v[34:35], v[34:35], v[12:13]
	v_pk_add_f32 v[36:37], v[36:37], v[14:15]
	v_pk_add_f32 v[34:35], v[34:35], v[8:9]
	v_pk_add_f32 v[36:37], v[36:37], v[20:21]
	v_pk_add_f32 v[34:35], v[34:35], v[28:29]
	v_pk_add_f32 v[36:37], v[36:37], v[30:31]
	v_min_u32_e32 v38, 13, v93
	v_pk_add_f32 v[36:37], v[36:37], v[40:41]
	v_pk_add_f32 v[34:35], v[34:35], v[26:27]
	v_pk_add_f32 v[36:37], v[36:37], v[48:49]
	v_add_u32_e32 v38, 3, v38
	v_pk_add_f32 v[32:33], v[32:33], v[24:25]
	v_pk_add_f32 v[34:35], v[34:35], v[46:47]
	v_pk_add_f32 v[36:37], v[36:37], v[50:51]
	v_cvt_f32_ubyte0_e32 v38, v38
	v_pk_add_f32 v[18:19], v[18:19], v[22:23]
	v_pk_add_f32 v[32:33], v[32:33], v[16:17]
	v_pk_add_f32 v[34:35], v[34:35], v[42:43]
	v_pk_add_f32 v[36:37], v[36:37], v[54:55]
	v_rcp_iflag_f32_e32 v38, v38
	v_pk_add_f32 v[18:19], v[18:19], v[4:5]
	v_pk_add_f32 v[32:33], v[32:33], v[10:11]
	v_pk_add_f32 v[34:35], v[34:35], v[52:53]
	v_pk_add_f32 v[36:37], v[36:37], v[74:75]
	v_pk_add_f32 v[18:19], v[18:19], v[6:7]
	v_pk_add_f32 v[32:33], v[32:33], v[2:3]
	s_waitcnt vmcnt(1)
	v_lshlrev_b32_e32 v84, 16, v83
	v_and_b32_e32 v85, 0xffff0000, v83
	v_pk_add_f32 v[34:35], v[34:35], v[70:71]
	v_pk_add_f32 v[36:37], v[36:37], v[80:81]
	v_pk_add_f32 v[18:19], v[18:19], v[0:1]
	v_pk_add_f32 v[32:33], v[32:33], v[14:15]
	v_lshlrev_b32_e32 v78, 16, v82
	v_and_b32_e32 v79, 0xffff0000, v82
	v_pk_add_f32 v[34:35], v[34:35], v[76:77]
	v_pk_add_f32 v[36:37], v[36:37], v[84:85]
	v_xor_b32_e32 v45, 0x80000000, v85
	v_xor_b32_e32 v44, 0x80000000, v84
	v_pk_add_f32 v[18:19], v[18:19], v[12:13]
	v_pk_add_f32 v[32:33], v[32:33], v[20:21]
	v_pk_add_f32 v[34:35], v[34:35], v[78:79]
	v_pk_fma_f32 v[36:37], v[38:39], v[36:37], v[44:45] op_sel_hi:[0,1,1]
	v_xor_b32_e32 v45, 0x80000000, v79
	v_xor_b32_e32 v44, 0x80000000, v78
	v_pk_add_f32 v[18:19], v[18:19], v[8:9]
	v_pk_add_f32 v[32:33], v[32:33], v[30:31]
	v_pk_fma_f32 v[34:35], v[38:39], v[34:35], v[44:45] op_sel_hi:[0,1,1]
	v_pk_add_f32 v[18:19], v[18:19], v[28:29]
	v_pk_add_f32 v[32:33], v[32:33], v[40:41]
	v_cvt_pk_bf16_f32 v34, v34, v35
	v_cvt_pk_bf16_f32 v35, v36, v37
	v_pk_add_f32 v[18:19], v[18:19], v[26:27]
	v_pk_add_f32 v[32:33], v[32:33], v[48:49]
	v_min_u32_e32 v36, 12, v93
	v_pk_add_f32 v[18:19], v[18:19], v[46:47]
	v_pk_add_f32 v[32:33], v[32:33], v[50:51]
	v_add_u32_e32 v36, 4, v36
	v_pk_add_f32 v[18:19], v[18:19], v[42:43]
	v_pk_add_f32 v[32:33], v[32:33], v[54:55]
	v_cvt_f32_ubyte0_e32 v36, v36
	v_pk_add_f32 v[18:19], v[18:19], v[52:53]
	v_pk_add_f32 v[32:33], v[32:33], v[74:75]
	v_rcp_iflag_f32_e32 v36, v36
	v_pk_add_f32 v[18:19], v[18:19], v[70:71]
	v_pk_add_f32 v[32:33], v[32:33], v[80:81]
	s_waitcnt vmcnt(0)
; #define LAS __attribute__((address_space(3)))
; DI unsigned pk2(float a, float b) { f32x2 v = {a, b}; nbf2 r = __builtin_convertvector(v, nbf2); return __builtin_bit_cast(unsigned, r); }
; template <int W>
; DI void pool_fill(LAS bf16_t* dA, const Args& a, int l, int g, int t0, int tid) {
;     ...
;         for (int j = 0; j < 8; ++j) { f32x4 sum = pv[j];
; #pragma unroll
;             for (int i = 1; i < W; ++i) sum += pv[j + i];
;             const int tp = tpos0 + j; const float inv = __builtin_amdgcn_rcpf((float)((tp + 1 < W) ? tp + 1 : W));
;             const f32x4 d = sum * inv - pv[j + W - 1]; u32x2 pw; pw.x = pk2(d[0], d[1]); pw.y = pk2(d[2], d[3]); *(LAS u32x2*)(dA + (lr0 + j) * 136 + c0) = pw; }
	v_lshlrev_b32_e32 v82, 16, v86
	v_and_b32_e32 v83, 0xffff0000, v86
	v_lshlrev_b32_e32 v86, 16, v87
	v_and_b32_e32 v87, 0xffff0000, v87
	v_pk_add_f32 v[18:19], v[18:19], v[76:77]
	v_pk_add_f32 v[32:33], v[32:33], v[84:85]
	v_pk_add_f32 v[18:19], v[18:19], v[78:79]
	v_pk_add_f32 v[32:33], v[32:33], v[86:87]
	v_xor_b32_e32 v39, 0x80000000, v87
	v_xor_b32_e32 v38, 0x80000000, v86
	v_pk_add_f32 v[18:19], v[18:19], v[82:83]
	v_pk_fma_f32 v[32:33], v[36:37], v[32:33], v[38:39] op_sel_hi:[0,1,1]
	v_xor_b32_e32 v39, 0x80000000, v83
	v_xor_b32_e32 v38, 0x80000000, v82
	v_pk_fma_f32 v[18:19], v[36:37], v[18:19], v[38:39] op_sel_hi:[0,1,1]
	v_cvt_pk_bf16_f32 v18, v18, v19
	v_cvt_pk_bf16_f32 v19, v32, v33
	ds_write2_b64 v97, v[34:35], v[18:19] offset0:68 offset1:102
	v_pk_add_f32 v[18:19], v[22:23], v[4:5]
	v_pk_add_f32 v[22:23], v[24:25], v[16:17]
	v_pk_add_f32 v[18:19], v[18:19], v[6:7]
	v_pk_add_f32 v[22:23], v[22:23], v[10:11]
	v_pk_add_f32 v[18:19], v[18:19], v[0:1]
	v_pk_add_f32 v[22:23], v[22:23], v[2:3]
	v_pk_add_f32 v[18:19], v[18:19], v[12:13]
	v_pk_add_f32 v[22:23], v[22:23], v[14:15]
	v_pk_add_f32 v[18:19], v[18:19], v[8:9]
	v_pk_add_f32 v[22:23], v[22:23], v[20:21]
	v_pk_add_f32 v[18:19], v[18:19], v[28:29]
	v_pk_add_f32 v[22:23], v[22:23], v[30:31]
	v_pk_add_f32 v[18:19], v[18:19], v[26:27]
	v_pk_add_f32 v[22:23], v[22:23], v[40:41]
	v_pk_add_f32 v[18:19], v[18:19], v[46:47]
	v_pk_add_f32 v[22:23], v[22:23], v[48:49]
	v_min_u32_e32 v24, 11, v93
	v_pk_add_f32 v[22:23], v[22:23], v[50:51]
	v_pk_add_f32 v[18:19], v[18:19], v[42:43]
	v_pk_add_f32 v[22:23], v[22:23], v[54:55]
	v_add_u32_e32 v24, 5, v24
	v_pk_add_f32 v[16:17], v[16:17], v[10:11]
	v_pk_add_f32 v[18:19], v[18:19], v[52:53]
	v_pk_add_f32 v[22:23], v[22:23], v[74:75]
	v_cvt_f32_ubyte0_e32 v24, v24
	v_pk_add_f32 v[4:5], v[4:5], v[6:7]
	v_pk_add_f32 v[16:17], v[16:17], v[2:3]
	v_pk_add_f32 v[18:19], v[18:19], v[70:71]
	v_pk_add_f32 v[22:23], v[22:23], v[80:81]
	v_rcp_iflag_f32_e32 v24, v24
	v_pk_add_f32 v[4:5], v[4:5], v[0:1]
	v_pk_add_f32 v[16:17], v[16:17], v[14:15]
	v_pk_add_f32 v[18:19], v[18:19], v[76:77]
	v_pk_add_f32 v[22:23], v[22:23], v[84:85]
	v_pk_add_f32 v[4:5], v[4:5], v[12:13]
	v_pk_add_f32 v[16:17], v[16:17], v[20:21]
	v_lshlrev_b32_e32 v64, 16, v63
	v_and_b32_e32 v65, 0xffff0000, v63
	v_pk_add_f32 v[18:19], v[18:19], v[78:79]
	v_pk_add_f32 v[22:23], v[22:23], v[86:87]
	v_pk_add_f32 v[4:5], v[4:5], v[8:9]
	v_pk_add_f32 v[16:17], v[16:17], v[30:31]
	v_lshlrev_b32_e32 v60, 16, v62
	v_and_b32_e32 v61, 0xffff0000, v62
	v_pk_add_f32 v[18:19], v[18:19], v[82:83]
	v_pk_add_f32 v[22:23], v[22:23], v[64:65]
	v_xor_b32_e32 v33, 0x80000000, v65
	v_xor_b32_e32 v32, 0x80000000, v64
	v_pk_add_f32 v[4:5], v[4:5], v[28:29]
	v_pk_add_f32 v[16:17], v[16:17], v[40:41]
	v_pk_add_f32 v[18:19], v[18:19], v[60:61]
	v_pk_fma_f32 v[22:23], v[24:25], v[22:23], v[32:33] op_sel_hi:[0,1,1]
	v_xor_b32_e32 v33, 0x80000000, v61
	v_xor_b32_e32 v32, 0x80000000, v60
	v_pk_add_f32 v[4:5], v[4:5], v[26:27]
	v_pk_add_f32 v[16:17], v[16:17], v[48:49]
	v_pk_fma_f32 v[18:19], v[24:25], v[18:19], v[32:33] op_sel_hi:[0,1,1]
	v_pk_add_f32 v[4:5], v[4:5], v[46:47]
	v_pk_add_f32 v[16:17], v[16:17], v[50:51]
	v_cvt_pk_bf16_f32 v18, v18, v19
	v_cvt_pk_bf16_f32 v19, v22, v23
	v_pk_add_f32 v[4:5], v[4:5], v[42:43]
	v_pk_add_f32 v[16:17], v[16:17], v[54:55]
	v_min_u32_e32 v22, 10, v93
	v_pk_add_f32 v[4:5], v[4:5], v[52:53]
	v_pk_add_f32 v[16:17], v[16:17], v[74:75]
	v_add_u32_e32 v22, 6, v22
	v_pk_add_f32 v[4:5], v[4:5], v[70:71]
	v_pk_add_f32 v[16:17], v[16:17], v[80:81]
	v_cvt_f32_ubyte0_e32 v22, v22
	v_pk_add_f32 v[4:5], v[4:5], v[76:77]
	v_pk_add_f32 v[16:17], v[16:17], v[84:85]
	v_rcp_iflag_f32_e32 v22, v22
	v_pk_add_f32 v[4:5], v[4:5], v[78:79]
	v_pk_add_f32 v[16:17], v[16:17], v[86:87]
	v_lshlrev_b32_e32 v68, 16, v67
	v_and_b32_e32 v69, 0xffff0000, v67
	v_pk_add_f32 v[4:5], v[4:5], v[82:83]
	v_pk_add_f32 v[16:17], v[16:17], v[64:65]
; #define LAS __attribute__((address_space(3)))
; DI unsigned pk2(float a, float b) { f32x2 v = {a, b}; nbf2 r = __builtin_convertvector(v, nbf2); return __builtin_bit_cast(unsigned, r); }
; template <int W>
; DI void pool_fill(LAS bf16_t* dA, const Args& a, int l, int g, int t0, int tid) {
;     ...
;         for (int j = 0; j < 8; ++j) { f32x4 sum = pv[j];
; #pragma unroll
;             for (int i = 1; i < W; ++i) sum += pv[j + i];
;             const int tp = tpos0 + j; const float inv = __builtin_amdgcn_rcpf((float)((tp + 1 < W) ? tp + 1 : W));
;             const f32x4 d = sum * inv - pv[j + W - 1]; u32x2 pw; pw.x = pk2(d[0], d[1]); pw.y = pk2(d[2], d[3]); *(LAS u32x2*)(dA + (lr0 + j) * 136 + c0) = pw; }
	v_lshlrev_b32_e32 v62, 16, v66
	v_and_b32_e32 v63, 0xffff0000, v66
	v_pk_add_f32 v[4:5], v[4:5], v[60:61]
	v_pk_add_f32 v[16:17], v[16:17], v[68:69]
	v_xor_b32_e32 v25, 0x80000000, v69
	v_xor_b32_e32 v24, 0x80000000, v68
	v_pk_add_f32 v[4:5], v[4:5], v[62:63]
	v_pk_fma_f32 v[16:17], v[22:23], v[16:17], v[24:25] op_sel_hi:[0,1,1]
	v_xor_b32_e32 v25, 0x80000000, v63
	v_xor_b32_e32 v24, 0x80000000, v62
	v_pk_fma_f32 v[4:5], v[22:23], v[4:5], v[24:25] op_sel_hi:[0,1,1]
	v_cvt_pk_bf16_f32 v4, v4, v5
	v_cvt_pk_bf16_f32 v5, v16, v17
	ds_write2_b64 v97, v[18:19], v[4:5] offset0:136 offset1:170
	v_pk_add_f32 v[4:5], v[6:7], v[0:1]
	v_pk_add_f32 v[6:7], v[10:11], v[2:3]
	v_pk_add_f32 v[4:5], v[4:5], v[12:13]
	v_pk_add_f32 v[6:7], v[6:7], v[14:15]
	v_pk_add_f32 v[4:5], v[4:5], v[8:9]
	v_pk_add_f32 v[6:7], v[6:7], v[20:21]
	v_pk_add_f32 v[4:5], v[4:5], v[28:29]
	v_pk_add_f32 v[6:7], v[6:7], v[30:31]
	v_pk_add_f32 v[4:5], v[4:5], v[26:27]
	v_pk_add_f32 v[6:7], v[6:7], v[40:41]
	v_pk_add_f32 v[4:5], v[4:5], v[46:47]
	v_pk_add_f32 v[6:7], v[6:7], v[48:49]
	v_pk_add_f32 v[4:5], v[4:5], v[42:43]
	v_pk_add_f32 v[6:7], v[6:7], v[50:51]
	v_pk_add_f32 v[4:5], v[4:5], v[52:53]
	v_pk_add_f32 v[6:7], v[6:7], v[54:55]
	v_min_u32_e32 v10, 9, v93
	v_pk_add_f32 v[6:7], v[6:7], v[74:75]
	v_pk_add_f32 v[4:5], v[4:5], v[70:71]
	v_pk_add_f32 v[6:7], v[6:7], v[80:81]
	v_add_u32_e32 v10, 7, v10
	v_pk_add_f32 v[4:5], v[4:5], v[76:77]
	v_pk_add_f32 v[6:7], v[6:7], v[84:85]
	v_cvt_f32_ubyte0_e32 v10, v10
	v_pk_add_f32 v[2:3], v[2:3], v[14:15]
	v_pk_add_f32 v[4:5], v[4:5], v[78:79]
	v_pk_add_f32 v[6:7], v[6:7], v[86:87]
	v_rcp_iflag_f32_e32 v10, v10
	v_pk_add_f32 v[0:1], v[0:1], v[12:13]
	v_pk_add_f32 v[2:3], v[2:3], v[20:21]
	v_pk_add_f32 v[4:5], v[4:5], v[82:83]
	v_pk_add_f32 v[6:7], v[6:7], v[64:65]
	v_pk_add_f32 v[0:1], v[0:1], v[8:9]
	v_pk_add_f32 v[2:3], v[2:3], v[30:31]
	v_lshlrev_b32_e32 v66, 16, v72
	v_and_b32_e32 v67, 0xffff0000, v72
	v_lshlrev_b32_e32 v72, 16, v73
	v_and_b32_e32 v73, 0xffff0000, v73
	v_pk_add_f32 v[4:5], v[4:5], v[60:61]
	v_pk_add_f32 v[6:7], v[6:7], v[68:69]
	v_pk_add_f32 v[0:1], v[0:1], v[28:29]
	v_pk_add_f32 v[2:3], v[2:3], v[40:41]
	v_pk_add_f32 v[4:5], v[4:5], v[62:63]
	v_pk_add_f32 v[6:7], v[6:7], v[72:73]
	v_xor_b32_e32 v17, 0x80000000, v73
	v_xor_b32_e32 v16, 0x80000000, v72
	v_pk_add_f32 v[0:1], v[0:1], v[26:27]
	v_pk_add_f32 v[2:3], v[2:3], v[48:49]
	v_pk_add_f32 v[4:5], v[4:5], v[66:67]
	v_pk_fma_f32 v[6:7], v[10:11], v[6:7], v[16:17] op_sel_hi:[0,1,1]
	v_xor_b32_e32 v17, 0x80000000, v67
	v_xor_b32_e32 v16, 0x80000000, v66
	v_pk_add_f32 v[0:1], v[0:1], v[46:47]
	v_pk_add_f32 v[2:3], v[2:3], v[50:51]
	v_pk_fma_f32 v[4:5], v[10:11], v[4:5], v[16:17] op_sel_hi:[0,1,1]
	v_pk_add_f32 v[0:1], v[0:1], v[42:43]
	v_pk_add_f32 v[2:3], v[2:3], v[54:55]
	v_cvt_pk_bf16_f32 v4, v4, v5
	v_cvt_pk_bf16_f32 v5, v6, v7
	v_pk_add_f32 v[0:1], v[0:1], v[52:53]
	v_pk_add_f32 v[2:3], v[2:3], v[74:75]
	ds_write_b64 v97, v[4:5] offset:1632
	v_pk_add_f32 v[0:1], v[0:1], v[70:71]
	v_pk_add_f32 v[2:3], v[2:3], v[80:81]
	v_min_u32_e32 v4, 8, v93
	v_pk_add_f32 v[0:1], v[0:1], v[76:77]
	v_pk_add_f32 v[2:3], v[2:3], v[84:85]
	v_add_u32_e32 v4, 8, v4
	v_pk_add_f32 v[0:1], v[0:1], v[78:79]
	v_pk_add_f32 v[2:3], v[2:3], v[86:87]
	v_cvt_f32_ubyte0_e32 v4, v4
	v_pk_add_f32 v[0:1], v[0:1], v[82:83]
	v_pk_add_f32 v[2:3], v[2:3], v[64:65]
	v_rcp_iflag_f32_e32 v4, v4
	v_pk_add_f32 v[0:1], v[0:1], v[60:61]
	v_pk_add_f32 v[2:3], v[2:3], v[68:69]
	v_pk_add_f32 v[0:1], v[0:1], v[62:63]
	v_pk_add_f32 v[2:3], v[2:3], v[72:73]
	v_pk_add_f32 v[0:1], v[0:1], v[66:67]
	v_pk_add_f32 v[2:3], v[2:3], v[58:59]
	v_xor_b32_e32 v7, 0x80000000, v59
	v_xor_b32_e32 v6, 0x80000000, v58
	v_pk_add_f32 v[0:1], v[0:1], v[56:57]
	v_pk_fma_f32 v[2:3], v[4:5], v[2:3], v[6:7] op_sel_hi:[0,1,1]
	v_xor_b32_e32 v7, 0x80000000, v57
	v_xor_b32_e32 v6, 0x80000000, v56
	v_pk_fma_f32 v[0:1], v[4:5], v[0:1], v[6:7] op_sel_hi:[0,1,1]

; #define LAS __attribute__((address_space(3)))
; DI unsigned pk2(float a, float b) { f32x2 v = {a, b}; nbf2 r = __builtin_convertvector(v, nbf2); return __builtin_bit_cast(unsigned, r); }
; DI float bflo(unsigned w) { return __uint_as_float(w << 16); }
; DI float bfhi(unsigned w) { return __uint_as_float(w & 0xffff0000u); }
; template <int W>
; DI void pool_fill(LAS bf16_t* dA, const Args& a, int l, int g, int t0, int tid) {
;     ...
;         const int tpos0 = row0 & 2047;
;         const bf16_t* pp = PROJ + (size_t)row0 * NPROJ + 2048 + g * 128 + c0;
;         f32x4 pv[W + 7];
; #pragma unroll
;         for (int i = 0; i < W + 7; ++i) { const int dr = i - (W - 1);
;             if (tpos0 + dr >= 0) { const u32x2 rw = *(const u32x2*)(pp + (long)dr * NPROJ); pv[i] = (f32x4){bflo(rw.x), bfhi(rw.x), bflo(rw.y), bfhi(rw.y)}; }
;             else pv[i] = (f32x4){0.f, 0.f, 0.f, 0.f}; }
; #pragma unroll
;         for (int j = 0; j < 8; ++j) { f32x4 sum = pv[j];
; #pragma unroll
;             for (int i = 1; i < W; ++i) sum += pv[j + i];
;             const int tp = tpos0 + j; const float inv = __builtin_amdgcn_rcpf((float)((tp + 1 < W) ? tp + 1 : W));
;             const f32x4 d = sum * inv - pv[j + W - 1]; u32x2 pw; pw.x = pk2(d[0], d[1]); pw.y = pk2(d[2], d[3]); *(LAS u32x2*)(dA + (lr0 + j) * 136 + c0) = pw; }
.LBB0_162:
	s_andn2_b64 vcc, exec, s[8:9]
	s_cbranch_vccnz .LBB0_178
	v_mov_b64_e32 v[0:1], s[72:73]
	v_mad_i64_i32 v[0:1], s[8:9], v91, s42, v[0:1]
	v_lshlrev_b32_e32 v128, 1, v90
	v_and_b32_e32 v56, 0x7f8, v91
	v_lshl_add_u64 v[0:1], v[0:1], 0, v[128:129]
	s_mov_b64 s[8:9], 0x1200
	v_lshl_add_u64 v[2:3], v[0:1], 0, s[8:9]
	v_cmp_ne_u32_e64 s[8:9], 0, v56
	v_mov_b32_e32 v12, 0
	v_mov_b32_e32 v28, 0
	v_mov_b32_e32 v29, 0
	v_mov_b32_e32 v0, 0
	v_mov_b32_e32 v1, 0
	v_mov_b32_e32 v102, 0
	v_mov_b32_e32 v103, 0
	s_and_saveexec_b64 s[14:15], s[8:9]
	s_cbranch_execz .LBB0_165
	v_add_co_u32_e32 v0, vcc, 0xffff8000, v2
	s_nop 1
	v_addc_co_u32_e32 v1, vcc, -1, v3, vcc
	global_load_dwordx2 v[102:103], v[0:1], off offset:-3072
.LBB0_165:
	s_or_b64 exec, exec, s[14:15]
	v_mov_b32_e32 v13, 0
	v_mov_b32_e32 v26, 0
	v_mov_b32_e32 v27, 0
	v_mov_b32_e32 v104, 0
	v_mov_b32_e32 v105, 0
	s_and_saveexec_b64 s[14:15], s[8:9]
	s_cbranch_execz .LBB0_167
	v_add_co_u32_e32 v4, vcc, 0xffff9000, v2
	s_nop 1
	v_addc_co_u32_e32 v5, vcc, -1, v3, vcc
	global_load_dwordx2 v[104:105], v[4:5], off offset:-2048
.LBB0_167:
	s_or_b64 exec, exec, s[14:15]
	v_mov_b32_e32 v6, 0
	v_mov_b32_e32 v22, 0
	v_mov_b32_e32 v23, 0
	v_mov_b32_e32 v24, 0
	v_mov_b32_e32 v25, 0
	v_mov_b32_e32 v106, 0
	v_mov_b32_e32 v107, 0
	s_and_saveexec_b64 s[14:15], s[8:9]
	s_cbranch_execz .LBB0_169
	v_add_co_u32_e32 v4, vcc, 0xffffa000, v2
	s_nop 1
	v_addc_co_u32_e32 v5, vcc, -1, v3, vcc
	global_load_dwordx2 v[106:107], v[4:5], off offset:-1024
.LBB0_169:
	s_or_b64 exec, exec, s[14:15]
	v_mov_b32_e32 v7, 0
	v_mov_b32_e32 v20, 0
	v_mov_b32_e32 v21, 0
	v_mov_b32_e32 v108, 0
	v_mov_b32_e32 v109, 0
	s_and_saveexec_b64 s[14:15], s[8:9]
	s_cbranch_execz .LBB0_171
	v_add_co_u32_e32 v4, vcc, 0xffffb000, v2
	s_nop 1
	v_addc_co_u32_e32 v5, vcc, -1, v3, vcc
	global_load_dwordx2 v[108:109], v[4:5], off
.LBB0_171:
	s_or_b64 exec, exec, s[14:15]
	v_mov_b32_e32 v4, 0
	v_mov_b32_e32 v16, 0
	v_mov_b32_e32 v17, 0
	v_mov_b32_e32 v18, 0
	v_mov_b32_e32 v19, 0
	v_mov_b32_e32 v110, 0
	v_mov_b32_e32 v111, 0
	s_and_saveexec_b64 s[14:15], s[8:9]
	s_cbranch_execz .LBB0_173
	v_add_co_u32_e32 v8, vcc, 0xffffd000, v2
	s_nop 1
	v_addc_co_u32_e32 v9, vcc, -1, v3, vcc
	global_load_dwordx2 v[110:111], v[8:9], off offset:-3072
.LBB0_173:
	s_or_b64 exec, exec, s[14:15]
	v_mov_b32_e32 v5, 0
	v_mov_b32_e32 v14, 0
	v_mov_b32_e32 v15, 0
	v_mov_b32_e32 v112, 0
	v_mov_b32_e32 v113, 0
	s_and_saveexec_b64 s[14:15], s[8:9]
	s_cbranch_execz .LBB0_175
	v_add_co_u32_e32 v4, vcc, 0xffffe000, v2
	s_nop 1
	v_addc_co_u32_e32 v5, vcc, -1, v3, vcc
	global_load_dwordx2 v[112:113], v[4:5], off offset:-2048
.LBB0_175:
	s_or_b64 exec, exec, s[14:15]
	v_mov_b32_e32 v8, 0
	v_mov_b32_e32 v57, 0x40e00000
	v_mov_b32_e32 v9, 0
	v_mov_b32_e32 v10, 0
	v_mov_b32_e32 v11, 0
	v_mov_b32_e32 v114, 0
	v_mov_b32_e32 v115, 0
	s_and_saveexec_b64 s[14:15], s[8:9]
	s_cbranch_execz .LBB0_177
	v_add_co_u32_e32 v8, vcc, 0xfffff000, v2
	v_mov_b32_e32 v57, 0x41000000
	s_nop 0
	v_addc_co_u32_e32 v9, vcc, -1, v3, vcc
	global_load_dwordx2 v[114:115], v[8:9], off offset:-1024
.LBB0_177:
	s_or_b64 exec, exec, s[14:15]
	s_waitcnt vmcnt(0)
	v_lshlrev_b32_e32 v28, 16, v102
	v_and_b32_e32 v29, 0xffff0000, v102
	v_lshlrev_b32_e32 v0, 16, v103
	v_and_b32_e32 v1, 0xffff0000, v103
	v_lshlrev_b32_e32 v12, 16, v104
	v_and_b32_e32 v13, 0xffff0000, v104
	v_lshlrev_b32_e32 v26, 16, v105
	v_and_b32_e32 v27, 0xffff0000, v105
	v_lshlrev_b32_e32 v22, 16, v106
	v_and_b32_e32 v23, 0xffff0000, v106
	v_lshlrev_b32_e32 v24, 16, v107
	v_and_b32_e32 v25, 0xffff0000, v107
	v_lshlrev_b32_e32 v6, 16, v108
	v_and_b32_e32 v7, 0xffff0000, v108
	v_lshlrev_b32_e32 v20, 16, v109
	v_and_b32_e32 v21, 0xffff0000, v109
	v_lshlrev_b32_e32 v16, 16, v110
	v_and_b32_e32 v17, 0xffff0000, v110
	v_lshlrev_b32_e32 v18, 16, v111
	v_and_b32_e32 v19, 0xffff0000, v111
	v_lshlrev_b32_e32 v4, 16, v112
	v_and_b32_e32 v5, 0xffff0000, v112
	v_lshlrev_b32_e32 v14, 16, v113
	v_and_b32_e32 v15, 0xffff0000, v113
	v_lshlrev_b32_e32 v8, 16, v114
	v_and_b32_e32 v9, 0xffff0000, v114
	v_lshlrev_b32_e32 v10, 16, v115
	v_and_b32_e32 v11, 0xffff0000, v115
	global_load_dwordx2 v[30:31], v[2:3], off
	v_add_co_u32_e32 v32, vcc, 0x1000, v2
	s_movk_i32 s8, 0x5000
	s_nop 0
	v_addc_co_u32_e32 v33, vcc, 0, v3, vcc
	v_add_co_u32_e32 v34, vcc, s8, v2
	s_movk_i32 s8, 0x6000
	s_nop 0
	v_addc_co_u32_e32 v35, vcc, 0, v3, vcc
	global_load_dwordx2 v[36:37], v[34:35], off
	v_add_co_u32_e32 v34, vcc, s8, v2
	s_movk_i32 s8, 0x7000
	s_nop 0
	v_addc_co_u32_e32 v35, vcc, 0, v3, vcc
	global_load_dwordx2 v[38:39], v[34:35], off offset:1024
	v_add_co_u32_e32 v34, vcc, s8, v2
	s_movk_i32 s8, 0x3000
	s_nop 0
	v_addc_co_u32_e32 v35, vcc, 0, v3, vcc
	global_load_dwordx2 v[42:43], v[34:35], off offset:2048
	v_add_co_u32_e32 v34, vcc, s49, v2
	v_pk_add_f32 v[0:1], v[0:1], v[26:27]
	s_nop 0
	v_addc_co_u32_e32 v35, vcc, 0, v3, vcc
	global_load_dwordx2 v[44:45], v[34:35], off offset:3072
	global_load_dwordx2 v[46:47], v[32:33], off offset:1024
	v_add_co_u32_e32 v32, vcc, s93, v2
	v_min_u32_e32 v62, 7, v56
	s_nop 0
	v_addc_co_u32_e32 v33, vcc, 0, v3, vcc
	global_load_dwordx2 v[50:51], v[32:33], off offset:2048
	v_add_co_u32_e32 v2, vcc, s8, v2
	v_pk_add_f32 v[0:1], v[0:1], v[24:25]
	s_nop 0
	v_addc_co_u32_e32 v3, vcc, 0, v3, vcc
	global_load_dwordx2 v[54:55], v[2:3], off offset:3072
	v_pk_add_f32 v[2:3], v[28:29], v[12:13]
	v_add_u32_e32 v62, 1, v62
	v_pk_add_f32 v[2:3], v[2:3], v[22:23]
	v_pk_add_f32 v[0:1], v[0:1], v[20:21]
	v_cvt_f32_ubyte0_e32 v62, v62
	v_pk_add_f32 v[2:3], v[2:3], v[6:7]
	v_pk_add_f32 v[0:1], v[0:1], v[18:19]
	v_rcp_iflag_f32_e32 v62, v62
	v_pk_add_f32 v[2:3], v[2:3], v[16:17]
	v_pk_add_f32 v[0:1], v[0:1], v[14:15]
	v_pk_add_f32 v[2:3], v[2:3], v[4:5]
	v_pk_add_f32 v[58:59], v[0:1], v[10:11]
	v_pk_add_f32 v[48:49], v[2:3], v[8:9]
	v_pk_add_f32 v[26:27], v[26:27], v[24:25]
	v_pk_add_f32 v[12:13], v[12:13], v[22:23]
	v_pk_add_f32 v[26:27], v[26:27], v[20:21]
	v_pk_add_f32 v[12:13], v[12:13], v[6:7]
	v_pk_add_f32 v[26:27], v[26:27], v[18:19]
	v_pk_add_f32 v[12:13], v[12:13], v[16:17]
	v_pk_add_f32 v[26:27], v[26:27], v[14:15]
	v_pk_add_f32 v[12:13], v[12:13], v[4:5]
	v_pk_add_f32 v[26:27], v[26:27], v[10:11]
	v_pk_add_f32 v[12:13], v[12:13], v[8:9]
	s_waitcnt vmcnt(7)
; #define LAS __attribute__((address_space(3)))
; DI unsigned pk2(float a, float b) { f32x2 v = {a, b}; nbf2 r = __builtin_convertvector(v, nbf2); return __builtin_bit_cast(unsigned, r); }
; template <int W>
; DI void pool_fill(LAS bf16_t* dA, const Args& a, int l, int g, int t0, int tid) {
;     ...
;         for (int j = 0; j < 8; ++j) { f32x4 sum = pv[j];
; #pragma unroll
;             for (int i = 1; i < W; ++i) sum += pv[j + i];
;             const int tp = tpos0 + j; const float inv = __builtin_amdgcn_rcpf((float)((tp + 1 < W) ? tp + 1 : W));
;             const f32x4 d = sum * inv - pv[j + W - 1]; u32x2 pw; pw.x = pk2(d[0], d[1]); pw.y = pk2(d[2], d[3]); *(LAS u32x2*)(dA + (lr0 + j) * 136 + c0) = pw; }
	v_lshlrev_b32_e32 v40, 16, v31
	v_and_b32_e32 v41, 0xffff0000, v31
	v_lshlrev_b32_e32 v34, 16, v30
	v_and_b32_e32 v35, 0xffff0000, v30
	v_pk_add_f32 v[58:59], v[58:59], v[40:41]
	v_xor_b32_e32 v65, 0x80000000, v41
	v_xor_b32_e32 v64, 0x80000000, v40
	v_pk_add_f32 v[60:61], v[48:49], v[34:35]
	v_pk_fma_f32 v[58:59], v[62:63], v[58:59], v[64:65] op_sel_hi:[0,1,1]
	v_xor_b32_e32 v65, 0x80000000, v35
	v_xor_b32_e32 v64, 0x80000000, v34
	v_pk_fma_f32 v[60:61], v[62:63], v[60:61], v[64:65] op_sel_hi:[0,1,1]
	v_cvt_pk_bf16_f32 v60, v60, v61
	v_cvt_pk_bf16_f32 v61, v58, v59
	v_mul_lo_u32 v58, v92, s47
	v_add3_u32 v59, 0, v128, v58
	v_min_u32_e32 v58, 6, v56
	v_add_u32_e32 v58, 2, v58
	v_cvt_f32_ubyte0_e32 v58, v58
	v_rcp_iflag_f32_e32 v58, v58
	v_pk_add_f32 v[26:27], v[26:27], v[40:41]
	v_pk_add_f32 v[12:13], v[12:13], v[34:35]
	s_waitcnt vmcnt(6)
	v_lshlrev_b32_e32 v32, 16, v37
	v_and_b32_e32 v33, 0xffff0000, v37
	v_lshlrev_b32_e32 v28, 16, v36
	v_and_b32_e32 v29, 0xffff0000, v36
	s_waitcnt vmcnt(5)
	v_lshlrev_b32_e32 v30, 16, v38
	v_and_b32_e32 v31, 0xffff0000, v38
	s_waitcnt vmcnt(3)
	v_lshlrev_b32_e32 v0, 16, v44
	s_waitcnt vmcnt(2)
	v_lshlrev_b32_e32 v48, 16, v47
	v_and_b32_e32 v49, 0xffff0000, v47
	v_and_b32_e32 v1, 0xffff0000, v44
	v_lshlrev_b32_e32 v2, 16, v45
	v_and_b32_e32 v3, 0xffff0000, v45
	v_lshlrev_b32_e32 v44, 16, v46
	v_and_b32_e32 v45, 0xffff0000, v46
	v_pk_add_f32 v[26:27], v[26:27], v[48:49]
	v_xor_b32_e32 v63, 0x80000000, v49
	v_xor_b32_e32 v62, 0x80000000, v48
	v_pk_add_f32 v[12:13], v[12:13], v[44:45]
	v_pk_fma_f32 v[26:27], v[58:59], v[26:27], v[62:63] op_sel_hi:[0,1,1]
	v_xor_b32_e32 v63, 0x80000000, v45
	v_xor_b32_e32 v62, 0x80000000, v44
	v_pk_fma_f32 v[12:13], v[58:59], v[12:13], v[62:63] op_sel_hi:[0,1,1]
	v_cvt_pk_bf16_f32 v12, v12, v13
	v_cvt_pk_bf16_f32 v13, v26, v27
	ds_write2_b64 v59, v[60:61], v[12:13] offset1:34
	v_pk_add_f32 v[12:13], v[22:23], v[6:7]
	v_pk_add_f32 v[22:23], v[24:25], v[20:21]
	v_min_u32_e32 v24, 5, v56
	v_pk_add_f32 v[22:23], v[22:23], v[18:19]
	v_add_u32_e32 v24, 3, v24
	v_pk_add_f32 v[12:13], v[12:13], v[16:17]
	v_pk_add_f32 v[22:23], v[22:23], v[14:15]
	v_cvt_f32_ubyte0_e32 v24, v24
	v_pk_add_f32 v[12:13], v[12:13], v[4:5]
	v_pk_add_f32 v[22:23], v[22:23], v[10:11]
	v_rcp_iflag_f32_e32 v24, v24
	v_pk_add_f32 v[12:13], v[12:13], v[8:9]
	v_pk_add_f32 v[22:23], v[22:23], v[40:41]
	s_waitcnt vmcnt(1)
	v_lshlrev_b32_e32 v52, 16, v51
	v_and_b32_e32 v53, 0xffff0000, v51
	v_pk_add_f32 v[12:13], v[12:13], v[34:35]
	v_pk_add_f32 v[22:23], v[22:23], v[48:49]
	v_lshlrev_b32_e32 v46, 16, v50
	v_and_b32_e32 v47, 0xffff0000, v50
	v_pk_add_f32 v[12:13], v[12:13], v[44:45]
	v_pk_add_f32 v[22:23], v[22:23], v[52:53]
	v_xor_b32_e32 v27, 0x80000000, v53
	v_xor_b32_e32 v26, 0x80000000, v52
	v_pk_add_f32 v[12:13], v[12:13], v[46:47]
	v_pk_fma_f32 v[22:23], v[24:25], v[22:23], v[26:27] op_sel_hi:[0,1,1]
	v_xor_b32_e32 v27, 0x80000000, v47
	v_xor_b32_e32 v26, 0x80000000, v46
	v_pk_fma_f32 v[12:13], v[24:25], v[12:13], v[26:27] op_sel_hi:[0,1,1]
	v_cvt_pk_bf16_f32 v12, v12, v13
	v_cvt_pk_bf16_f32 v13, v22, v23
	v_pk_add_f32 v[20:21], v[20:21], v[18:19]
	v_min_u32_e32 v22, 4, v56
	v_pk_add_f32 v[6:7], v[6:7], v[16:17]
	v_pk_add_f32 v[20:21], v[20:21], v[14:15]
	v_add_u32_e32 v22, 4, v22
	v_pk_add_f32 v[6:7], v[6:7], v[4:5]
	v_pk_add_f32 v[20:21], v[20:21], v[10:11]
	v_cvt_f32_ubyte0_e32 v22, v22
	v_pk_add_f32 v[6:7], v[6:7], v[8:9]
	v_pk_add_f32 v[20:21], v[20:21], v[40:41]
	v_rcp_iflag_f32_e32 v22, v22
	v_pk_add_f32 v[6:7], v[6:7], v[34:35]
	v_pk_add_f32 v[20:21], v[20:21], v[48:49]
	s_waitcnt vmcnt(0)
; #define LAS __attribute__((address_space(3)))
; DI unsigned pk2(float a, float b) { f32x2 v = {a, b}; nbf2 r = __builtin_convertvector(v, nbf2); return __builtin_bit_cast(unsigned, r); }
; template <int W>
; DI void pool_fill(LAS bf16_t* dA, const Args& a, int l, int g, int t0, int tid) {
;     ...
;         for (int j = 0; j < 8; ++j) { f32x4 sum = pv[j];
; #pragma unroll
;             for (int i = 1; i < W; ++i) sum += pv[j + i];
;             const int tp = tpos0 + j; const float inv = __builtin_amdgcn_rcpf((float)((tp + 1 < W) ? tp + 1 : W));
;             const f32x4 d = sum * inv - pv[j + W - 1]; u32x2 pw; pw.x = pk2(d[0], d[1]); pw.y = pk2(d[2], d[3]); *(LAS u32x2*)(dA + (lr0 + j) * 136 + c0) = pw; }
	v_lshlrev_b32_e32 v50, 16, v54
	v_and_b32_e32 v51, 0xffff0000, v54
	v_lshlrev_b32_e32 v54, 16, v55
	v_and_b32_e32 v55, 0xffff0000, v55
	v_pk_add_f32 v[6:7], v[6:7], v[44:45]
	v_pk_add_f32 v[20:21], v[20:21], v[52:53]
	v_pk_add_f32 v[6:7], v[6:7], v[46:47]
	v_pk_add_f32 v[20:21], v[20:21], v[54:55]
	v_xor_b32_e32 v25, 0x80000000, v55
	v_xor_b32_e32 v24, 0x80000000, v54
	v_pk_add_f32 v[6:7], v[6:7], v[50:51]
	v_pk_fma_f32 v[20:21], v[22:23], v[20:21], v[24:25] op_sel_hi:[0,1,1]
	v_xor_b32_e32 v25, 0x80000000, v51
	v_xor_b32_e32 v24, 0x80000000, v50
	v_pk_fma_f32 v[6:7], v[22:23], v[6:7], v[24:25] op_sel_hi:[0,1,1]
	v_cvt_pk_bf16_f32 v6, v6, v7
	v_cvt_pk_bf16_f32 v7, v20, v21
	ds_write2_b64 v59, v[12:13], v[6:7] offset0:68 offset1:102
	v_pk_add_f32 v[6:7], v[16:17], v[4:5]
	v_pk_add_f32 v[12:13], v[18:19], v[14:15]
	v_min_u32_e32 v16, 3, v56
	v_pk_add_f32 v[12:13], v[12:13], v[10:11]
	v_add_u32_e32 v16, 5, v16
	v_pk_add_f32 v[6:7], v[6:7], v[8:9]
	v_pk_add_f32 v[12:13], v[12:13], v[40:41]
	v_cvt_f32_ubyte0_e32 v16, v16
	v_pk_add_f32 v[6:7], v[6:7], v[34:35]
	v_pk_add_f32 v[12:13], v[12:13], v[48:49]
	v_rcp_iflag_f32_e32 v16, v16
	v_pk_add_f32 v[6:7], v[6:7], v[44:45]
	v_pk_add_f32 v[12:13], v[12:13], v[52:53]
	v_pk_add_f32 v[6:7], v[6:7], v[46:47]
	v_pk_add_f32 v[12:13], v[12:13], v[54:55]
	v_pk_add_f32 v[6:7], v[6:7], v[50:51]
	v_pk_add_f32 v[12:13], v[12:13], v[32:33]
	v_xor_b32_e32 v19, 0x80000000, v33
	v_xor_b32_e32 v18, 0x80000000, v32
	v_pk_add_f32 v[6:7], v[6:7], v[28:29]
	v_pk_fma_f32 v[12:13], v[16:17], v[12:13], v[18:19] op_sel_hi:[0,1,1]
	v_xor_b32_e32 v19, 0x80000000, v29
	v_xor_b32_e32 v18, 0x80000000, v28
	v_pk_fma_f32 v[6:7], v[16:17], v[6:7], v[18:19] op_sel_hi:[0,1,1]
	v_cvt_pk_bf16_f32 v6, v6, v7
	v_cvt_pk_bf16_f32 v7, v12, v13
	v_pk_add_f32 v[12:13], v[14:15], v[10:11]
	v_min_u32_e32 v14, 2, v56
	v_pk_add_f32 v[4:5], v[4:5], v[8:9]
	v_pk_add_f32 v[12:13], v[12:13], v[40:41]
	v_add_u32_e32 v14, 6, v14
	v_pk_add_f32 v[4:5], v[4:5], v[34:35]
	v_pk_add_f32 v[12:13], v[12:13], v[48:49]
	v_cvt_f32_ubyte0_e32 v14, v14
	v_pk_add_f32 v[4:5], v[4:5], v[44:45]
	v_pk_add_f32 v[12:13], v[12:13], v[52:53]
	v_rcp_iflag_f32_e32 v14, v14
	v_pk_add_f32 v[4:5], v[4:5], v[46:47]
	v_pk_add_f32 v[12:13], v[12:13], v[54:55]
	v_lshlrev_b32_e32 v38, 16, v39
	v_and_b32_e32 v39, 0xffff0000, v39
	v_pk_add_f32 v[4:5], v[4:5], v[50:51]
	v_pk_add_f32 v[12:13], v[12:13], v[32:33]
	v_pk_add_f32 v[4:5], v[4:5], v[28:29]
	v_pk_add_f32 v[12:13], v[12:13], v[38:39]
	v_xor_b32_e32 v17, 0x80000000, v39
	v_xor_b32_e32 v16, 0x80000000, v38
	v_pk_add_f32 v[4:5], v[4:5], v[30:31]
	v_pk_fma_f32 v[12:13], v[14:15], v[12:13], v[16:17] op_sel_hi:[0,1,1]
	v_xor_b32_e32 v17, 0x80000000, v31
	v_xor_b32_e32 v16, 0x80000000, v30
	v_pk_fma_f32 v[4:5], v[14:15], v[4:5], v[16:17] op_sel_hi:[0,1,1]
	v_cvt_pk_bf16_f32 v4, v4, v5
	v_cvt_pk_bf16_f32 v5, v12, v13
	ds_write2_b64 v59, v[6:7], v[4:5] offset0:136 offset1:170
	v_pk_add_f32 v[6:7], v[10:11], v[40:41]
	v_pk_add_f32 v[4:5], v[8:9], v[34:35]
	v_pk_add_f32 v[6:7], v[6:7], v[48:49]
	v_pk_add_f32 v[4:5], v[4:5], v[44:45]
	v_pk_add_f32 v[6:7], v[6:7], v[52:53]
	v_pk_add_f32 v[4:5], v[4:5], v[46:47]
	v_pk_add_f32 v[6:7], v[6:7], v[54:55]
	v_rcp_f32_e32 v8, v57
	v_pk_add_f32 v[4:5], v[4:5], v[50:51]
	v_pk_add_f32 v[6:7], v[6:7], v[32:33]
	v_lshlrev_b32_e32 v36, 16, v42
	v_and_b32_e32 v37, 0xffff0000, v42
	v_lshlrev_b32_e32 v42, 16, v43
	v_and_b32_e32 v43, 0xffff0000, v43
	v_pk_add_f32 v[4:5], v[4:5], v[28:29]
	v_pk_add_f32 v[6:7], v[6:7], v[38:39]
	v_pk_add_f32 v[4:5], v[4:5], v[30:31]
	v_pk_add_f32 v[6:7], v[6:7], v[42:43]
	v_xor_b32_e32 v11, 0x80000000, v43
	v_xor_b32_e32 v10, 0x80000000, v42
	v_pk_add_f32 v[4:5], v[4:5], v[36:37]
	v_pk_fma_f32 v[6:7], v[8:9], v[6:7], v[10:11] op_sel_hi:[0,1,1]
	v_xor_b32_e32 v11, 0x80000000, v37
	v_xor_b32_e32 v10, 0x80000000, v36
	v_pk_fma_f32 v[4:5], v[8:9], v[4:5], v[10:11] op_sel_hi:[0,1,1]
	v_cvt_pk_bf16_f32 v4, v4, v5
	v_cvt_pk_bf16_f32 v5, v6, v7
	ds_write_b64 v59, v[4:5] offset:1632
	v_pk_add_f32 v[4:5], v[40:41], v[48:49]
	v_pk_add_f32 v[6:7], v[34:35], v[44:45]
	v_pk_add_f32 v[4:5], v[4:5], v[52:53]
	v_pk_add_f32 v[6:7], v[6:7], v[46:47]
	v_pk_add_f32 v[4:5], v[4:5], v[54:55]
	v_pk_add_f32 v[6:7], v[6:7], v[50:51]
	v_pk_add_f32 v[4:5], v[4:5], v[32:33]
	v_pk_add_f32 v[6:7], v[6:7], v[28:29]
	v_pk_add_f32 v[4:5], v[4:5], v[38:39]
	v_pk_add_f32 v[6:7], v[6:7], v[30:31]
	v_pk_add_f32 v[4:5], v[4:5], v[42:43]
	v_pk_add_f32 v[8:9], v[6:7], v[36:37]
	v_pk_add_f32 v[6:7], v[4:5], v[2:3]
	v_pk_add_f32 v[4:5], v[8:9], v[0:1]

; #define LAS __attribute__((address_space(3)))
; DI unsigned pk2(float a, float b) { f32x2 v = {a, b}; nbf2 r = __builtin_convertvector(v, nbf2); return __builtin_bit_cast(unsigned, r); }
; DI float bflo(unsigned w) { return __uint_as_float(w << 16); }
; DI float bfhi(unsigned w) { return __uint_as_float(w & 0xffff0000u); }
; template <int W>
; DI void pool_fill(LAS bf16_t* dA, const Args& a, int l, int g, int t0, int tid) {
;     ...
;         const int tpos0 = row0 & 2047;
;         const bf16_t* pp = PROJ + (size_t)row0 * NPROJ + 2048 + g * 128 + c0;
;         f32x4 pv[W + 7];
; #pragma unroll
;         for (int i = 0; i < W + 7; ++i) { const int dr = i - (W - 1);
;             if (tpos0 + dr >= 0) { const u32x2 rw = *(const u32x2*)(pp + (long)dr * NPROJ); pv[i] = (f32x4){bflo(rw.x), bfhi(rw.x), bflo(rw.y), bfhi(rw.y)}; }
;             else pv[i] = (f32x4){0.f, 0.f, 0.f, 0.f}; }
; #pragma unroll
;         for (int j = 0; j < 8; ++j) { f32x4 sum = pv[j];
; #pragma unroll
;             for (int i = 1; i < W; ++i) sum += pv[j + i];
;             const int tp = tpos0 + j; const float inv = __builtin_amdgcn_rcpf((float)((tp + 1 < W) ? tp + 1 : W));
;             const f32x4 d = sum * inv - pv[j + W - 1]; u32x2 pw; pw.x = pk2(d[0], d[1]); pw.y = pk2(d[2], d[3]); *(LAS u32x2*)(dA + (lr0 + j) * 136 + c0) = pw; }
.LBB0_184:
	s_andn2_b64 vcc, exec, s[12:13]
	s_cbranch_vccnz .LBB0_188
	v_mov_b64_e32 v[0:1], s[72:73]
	v_mad_i64_i32 v[0:1], s[12:13], v91, s42, v[0:1]
	v_lshlrev_b32_e32 v128, 1, v90
	v_and_b32_e32 v2, 0x7f8, v91
	v_lshl_add_u64 v[0:1], v[0:1], 0, v[128:129]
	v_lshl_add_u64 v[4:5], v[0:1], 0, s[84:85]
	v_cmp_ne_u32_e32 vcc, 0, v2
	v_mov_b32_e32 v0, 0
	v_mov_b32_e32 v6, 1.0
	v_mov_b32_e32 v1, 0
	v_mov_b32_e32 v2, 0
	v_mov_b32_e32 v3, 0
	v_mov_b32_e32 v102, 0
	v_mov_b32_e32 v103, 0
	s_and_saveexec_b64 s[12:13], vcc
	s_cbranch_execz .LBB0_187
	v_add_co_u32_e32 v0, vcc, 0xfffff000, v4
	v_mov_b32_e32 v6, 2.0
	s_nop 0
	v_addc_co_u32_e32 v1, vcc, -1, v5, vcc
	global_load_dwordx2 v[102:103], v[0:1], off offset:-1024
.LBB0_187:
	s_or_b64 exec, exec, s[12:13]
	s_waitcnt vmcnt(0)
	v_lshlrev_b32_e32 v0, 16, v102
	v_and_b32_e32 v1, 0xffff0000, v102
	v_lshlrev_b32_e32 v2, 16, v103
	v_and_b32_e32 v3, 0xffff0000, v103
	s_movk_i32 s12, 0x5000
	v_add_co_u32_e32 v10, vcc, s12, v4
	s_movk_i32 s12, 0x6000
	s_nop 0
	v_addc_co_u32_e32 v11, vcc, 0, v5, vcc
	v_add_co_u32_e32 v12, vcc, s12, v4
	s_movk_i32 s12, 0x7000
	s_nop 0
	v_addc_co_u32_e32 v13, vcc, 0, v5, vcc
	v_add_co_u32_e32 v14, vcc, s12, v4
	global_load_dwordx2 v[8:9], v[4:5], off
	s_nop 0
	v_addc_co_u32_e32 v15, vcc, 0, v5, vcc
	v_add_co_u32_e32 v16, vcc, s49, v4
	global_load_dwordx2 v[10:11], v[10:11], off
	s_nop 0
	v_addc_co_u32_e32 v17, vcc, 0, v5, vcc
	v_add_co_u32_e32 v18, vcc, 0x1000, v4
	global_load_dwordx2 v[12:13], v[12:13], off offset:1024
	s_nop 0
	v_addc_co_u32_e32 v19, vcc, 0, v5, vcc
	global_load_dwordx2 v[14:15], v[14:15], off offset:2048
	v_add_co_u32_e32 v20, vcc, s93, v4
	global_load_dwordx2 v[16:17], v[16:17], off offset:3072
	s_nop 0
	v_addc_co_u32_e32 v21, vcc, 0, v5, vcc
	global_load_dwordx2 v[18:19], v[18:19], off offset:1024
	s_movk_i32 s12, 0x3000
	global_load_dwordx2 v[20:21], v[20:21], off offset:2048
	v_add_co_u32_e32 v4, vcc, s12, v4
	v_rcp_f32_e32 v6, v6
	s_nop 0
	v_addc_co_u32_e32 v5, vcc, 0, v5, vcc
	global_load_dwordx2 v[4:5], v[4:5], off offset:3072
	v_mul_lo_u32 v7, v92, s47
	v_add3_u32 v38, 0, v128, v7
	s_waitcnt vmcnt(7)
	v_lshlrev_b32_e32 v22, 16, v8
	v_and_b32_e32 v23, 0xffff0000, v8
	v_lshlrev_b32_e32 v8, 16, v9
	v_and_b32_e32 v9, 0xffff0000, v9
	v_pk_add_f32 v[24:25], v[0:1], v[22:23]
	v_pk_add_f32 v[26:27], v[2:3], v[8:9]
	v_xor_b32_e32 v29, 0x80000000, v9
	v_xor_b32_e32 v28, 0x80000000, v8
	v_xor_b32_e32 v31, 0x80000000, v23
	v_xor_b32_e32 v30, 0x80000000, v22
	s_waitcnt vmcnt(6)
	v_lshlrev_b32_e32 v32, 16, v10
	v_and_b32_e32 v33, 0xffff0000, v10
	v_lshlrev_b32_e32 v10, 16, v11
	v_and_b32_e32 v11, 0xffff0000, v11
	s_waitcnt vmcnt(5)
	v_lshlrev_b32_e32 v34, 16, v12
	v_and_b32_e32 v35, 0xffff0000, v12
	s_waitcnt vmcnt(3)
	v_lshlrev_b32_e32 v0, 16, v16
	v_and_b32_e32 v1, 0xffff0000, v16
	v_lshlrev_b32_e32 v2, 16, v17
	v_and_b32_e32 v3, 0xffff0000, v17
	v_pk_fma_f32 v[16:17], v[6:7], v[26:27], v[28:29] op_sel_hi:[0,1,1]
	v_pk_fma_f32 v[6:7], v[6:7], v[24:25], v[30:31] op_sel_hi:[0,1,1]
	s_waitcnt vmcnt(2)
	v_lshlrev_b32_e32 v24, 16, v18
	v_and_b32_e32 v25, 0xffff0000, v18
	v_lshlrev_b32_e32 v18, 16, v19
	v_and_b32_e32 v19, 0xffff0000, v19
	v_pk_add_f32 v[8:9], v[8:9], v[18:19]
	v_xor_b32_e32 v29, 0x80000000, v19
	v_xor_b32_e32 v28, 0x80000000, v18
	v_pk_add_f32 v[22:23], v[22:23], v[24:25]
	v_pk_fma_f32 v[8:9], v[8:9], 0.5, v[28:29] op_sel_hi:[1,0,1]
	v_xor_b32_e32 v29, 0x80000000, v25
	v_xor_b32_e32 v28, 0x80000000, v24
	v_cvt_pk_bf16_f32 v6, v6, v7
	v_cvt_pk_bf16_f32 v7, v16, v17
	s_waitcnt vmcnt(1)
	v_lshlrev_b32_e32 v16, 16, v20
	v_and_b32_e32 v17, 0xffff0000, v20
	v_lshlrev_b32_e32 v20, 16, v21
	v_and_b32_e32 v21, 0xffff0000, v21
	v_pk_fma_f32 v[22:23], v[22:23], 0.5, v[28:29] op_sel_hi:[1,0,1]
	s_waitcnt vmcnt(0)
	v_lshlrev_b32_e32 v26, 16, v4
	v_cvt_pk_bf16_f32 v22, v22, v23
	v_cvt_pk_bf16_f32 v23, v8, v9
	v_pk_add_f32 v[8:9], v[18:19], v[20:21]
	v_xor_b32_e32 v19, 0x80000000, v21
	v_xor_b32_e32 v18, 0x80000000, v20
	ds_write2_b64 v38, v[6:7], v[22:23] offset1:34
	v_pk_add_f32 v[6:7], v[24:25], v[16:17]
	v_pk_fma_f32 v[8:9], v[8:9], 0.5, v[18:19] op_sel_hi:[1,0,1]
	v_xor_b32_e32 v19, 0x80000000, v17
	v_xor_b32_e32 v18, 0x80000000, v16
	v_and_b32_e32 v27, 0xffff0000, v4
	v_lshlrev_b32_e32 v4, 16, v5
	v_and_b32_e32 v5, 0xffff0000, v5
	v_pk_fma_f32 v[6:7], v[6:7], 0.5, v[18:19] op_sel_hi:[1,0,1]
	v_xor_b32_e32 v19, 0x80000000, v5
	v_cvt_pk_bf16_f32 v6, v6, v7
	v_cvt_pk_bf16_f32 v7, v8, v9
	v_pk_add_f32 v[8:9], v[16:17], v[26:27]
	v_pk_add_f32 v[16:17], v[20:21], v[4:5]
	v_xor_b32_e32 v18, 0x80000000, v4
	v_pk_fma_f32 v[16:17], v[16:17], 0.5, v[18:19] op_sel_hi:[1,0,1]
	v_xor_b32_e32 v19, 0x80000000, v27
	v_xor_b32_e32 v18, 0x80000000, v26
	v_pk_fma_f32 v[8:9], v[8:9], 0.5, v[18:19] op_sel_hi:[1,0,1]
	v_pk_add_f32 v[4:5], v[4:5], v[10:11]
	v_cvt_pk_bf16_f32 v8, v8, v9
	v_cvt_pk_bf16_f32 v9, v16, v17
	ds_write2_b64 v38, v[6:7], v[8:9] offset0:68 offset1:102
	v_xor_b32_e32 v9, 0x80000000, v11
	v_xor_b32_e32 v8, 0x80000000, v10
	v_lshlrev_b32_e32 v12, 16, v13
	v_and_b32_e32 v13, 0xffff0000, v13
	v_pk_add_f32 v[6:7], v[26:27], v[32:33]
	v_pk_fma_f32 v[4:5], v[4:5], 0.5, v[8:9] op_sel_hi:[1,0,1]
	v_xor_b32_e32 v9, 0x80000000, v33
	v_xor_b32_e32 v8, 0x80000000, v32
	v_pk_fma_f32 v[6:7], v[6:7], 0.5, v[8:9] op_sel_hi:[1,0,1]
	v_pk_add_f32 v[8:9], v[10:11], v[12:13]
	v_xor_b32_e32 v11, 0x80000000, v13
	v_xor_b32_e32 v10, 0x80000000, v12
	v_cvt_pk_bf16_f32 v6, v6, v7
	v_cvt_pk_bf16_f32 v7, v4, v5
	v_pk_add_f32 v[4:5], v[32:33], v[34:35]
	v_pk_fma_f32 v[8:9], v[8:9], 0.5, v[10:11] op_sel_hi:[1,0,1]
	v_xor_b32_e32 v11, 0x80000000, v35
	v_xor_b32_e32 v10, 0x80000000, v34
	v_pk_fma_f32 v[4:5], v[4:5], 0.5, v[10:11] op_sel_hi:[1,0,1]
	v_lshlrev_b32_e32 v36, 16, v14
	v_and_b32_e32 v37, 0xffff0000, v14
	v_lshlrev_b32_e32 v14, 16, v15
	v_and_b32_e32 v15, 0xffff0000, v15
	v_cvt_pk_bf16_f32 v4, v4, v5
	v_cvt_pk_bf16_f32 v5, v8, v9
	ds_write2_b64 v38, v[6:7], v[4:5] offset0:136 offset1:170
	v_pk_add_f32 v[6:7], v[12:13], v[14:15]
	v_xor_b32_e32 v9, 0x80000000, v15
	v_xor_b32_e32 v8, 0x80000000, v14
	v_pk_add_f32 v[4:5], v[34:35], v[36:37]
	v_pk_fma_f32 v[6:7], v[6:7], 0.5, v[8:9] op_sel_hi:[1,0,1]
	v_xor_b32_e32 v9, 0x80000000, v37
	v_xor_b32_e32 v8, 0x80000000, v36
	v_pk_fma_f32 v[4:5], v[4:5], 0.5, v[8:9] op_sel_hi:[1,0,1]
	s_nop 0
	v_cvt_pk_bf16_f32 v4, v4, v5
	v_cvt_pk_bf16_f32 v5, v6, v7
	ds_write_b64 v38, v[4:5] offset:1632
	v_pk_add_f32 v[6:7], v[14:15], v[2:3]
	v_pk_add_f32 v[4:5], v[36:37], v[0:1]

; #define LAS __attribute__((address_space(3)))
; DI unsigned pk2(float a, float b) { f32x2 v = {a, b}; nbf2 r = __builtin_convertvector(v, nbf2); return __builtin_bit_cast(unsigned, r); }
; DI float bflo(unsigned w) { return __uint_as_float(w << 16); }
; DI float bfhi(unsigned w) { return __uint_as_float(w & 0xffff0000u); }
; template <int W>
; DI void pool_fill(LAS bf16_t* dA, const Args& a, int l, int g, int t0, int tid) {
;     ...
;         const int tpos0 = row0 & 2047;
;         const bf16_t* pp = PROJ + (size_t)row0 * NPROJ + 2048 + g * 128 + c0;
;         f32x4 pv[W + 7];
; #pragma unroll
;         for (int i = 0; i < W + 7; ++i) { const int dr = i - (W - 1);
;             if (tpos0 + dr >= 0) { const u32x2 rw = *(const u32x2*)(pp + (long)dr * NPROJ); pv[i] = (f32x4){bflo(rw.x), bfhi(rw.x), bflo(rw.y), bfhi(rw.y)}; }
;             else pv[i] = (f32x4){0.f, 0.f, 0.f, 0.f}; }
; #pragma unroll
;         for (int j = 0; j < 8; ++j) { f32x4 sum = pv[j];
; #pragma unroll
;             for (int i = 1; i < W; ++i) sum += pv[j + i];
;             const int tp = tpos0 + j; const float inv = __builtin_amdgcn_rcpf((float)((tp + 1 < W) ? tp + 1 : W));
;             const f32x4 d = sum * inv - pv[j + W - 1]; u32x2 pw; pw.x = pk2(d[0], d[1]); pw.y = pk2(d[2], d[3]); *(LAS u32x2*)(dA + (lr0 + j) * 136 + c0) = pw; }
.LBB0_192:
	s_andn2_b64 vcc, exec, s[12:13]
	s_cbranch_vccnz .LBB0_200
	v_mov_b64_e32 v[0:1], s[72:73]
	v_mad_i64_i32 v[0:1], s[8:9], v91, s42, v[0:1]
	v_lshlrev_b32_e32 v128, 1, v90
	v_and_b32_e32 v25, 0x7f8, v91
	v_lshl_add_u64 v[0:1], v[0:1], 0, v[128:129]
	s_mov_b64 s[8:9], 0x1100
	v_lshl_add_u64 v[2:3], v[0:1], 0, s[8:9]
	v_cmp_ne_u32_e64 s[8:9], 0, v25
	v_mov_b32_e32 v4, 0
	v_mov_b32_e32 v12, 0
	v_mov_b32_e32 v13, 0
	v_mov_b32_e32 v0, 0
	v_mov_b32_e32 v1, 0
	v_mov_b32_e32 v102, 0
	v_mov_b32_e32 v103, 0
	s_and_saveexec_b64 s[12:13], s[8:9]
	s_cbranch_execz .LBB0_195
	v_add_co_u32_e32 v0, vcc, 0xffffd000, v2
	s_nop 1
	v_addc_co_u32_e32 v1, vcc, -1, v3, vcc
	global_load_dwordx2 v[102:103], v[0:1], off offset:-3072
.LBB0_195:
	s_or_b64 exec, exec, s[12:13]
	v_mov_b32_e32 v5, 0
	v_mov_b32_e32 v8, 0
	v_mov_b32_e32 v9, 0
	v_mov_b32_e32 v104, 0
	v_mov_b32_e32 v105, 0
	s_and_saveexec_b64 s[12:13], s[8:9]
	s_cbranch_execz .LBB0_197
	v_add_co_u32_e32 v4, vcc, 0xffffe000, v2
	s_nop 1
	v_addc_co_u32_e32 v5, vcc, -1, v3, vcc
	global_load_dwordx2 v[104:105], v[4:5], off offset:-2048
.LBB0_197:
	s_or_b64 exec, exec, s[12:13]
	v_mov_b32_e32 v6, 0
	v_mov_b32_e32 v26, 0x40400000
	v_mov_b32_e32 v7, 0
	v_mov_b32_e32 v10, 0
	v_mov_b32_e32 v11, 0
	v_mov_b32_e32 v106, 0
	v_mov_b32_e32 v107, 0
	s_and_saveexec_b64 s[12:13], s[8:9]
	s_cbranch_execz .LBB0_199
	v_add_co_u32_e32 v6, vcc, 0xfffff000, v2
	v_mov_b32_e32 v26, 4.0
	s_nop 0
	v_addc_co_u32_e32 v7, vcc, -1, v3, vcc
	global_load_dwordx2 v[106:107], v[6:7], off offset:-1024
.LBB0_199:
	s_or_b64 exec, exec, s[12:13]
	s_waitcnt vmcnt(0)
	v_lshlrev_b32_e32 v12, 16, v102
	v_and_b32_e32 v13, 0xffff0000, v102
	v_lshlrev_b32_e32 v0, 16, v103
	v_and_b32_e32 v1, 0xffff0000, v103
	v_lshlrev_b32_e32 v4, 16, v104
	v_and_b32_e32 v5, 0xffff0000, v104
	v_lshlrev_b32_e32 v8, 16, v105
	v_and_b32_e32 v9, 0xffff0000, v105
	v_lshlrev_b32_e32 v6, 16, v106
	v_and_b32_e32 v7, 0xffff0000, v106
	v_lshlrev_b32_e32 v10, 16, v107
	v_and_b32_e32 v11, 0xffff0000, v107
	s_movk_i32 s8, 0x5000
	v_add_co_u32_e32 v16, vcc, s8, v2
	s_movk_i32 s8, 0x6000
	s_nop 0
	v_addc_co_u32_e32 v17, vcc, 0, v3, vcc
	v_add_co_u32_e32 v18, vcc, s8, v2
	s_movk_i32 s8, 0x7000
	s_nop 0
	v_addc_co_u32_e32 v19, vcc, 0, v3, vcc
	v_add_co_u32_e32 v20, vcc, s8, v2
	global_load_dwordx2 v[18:19], v[18:19], off offset:1024
	s_nop 0
	v_addc_co_u32_e32 v21, vcc, 0, v3, vcc
	global_load_dwordx2 v[22:23], v[20:21], off offset:2048
	v_add_co_u32_e32 v20, vcc, s49, v2
	global_load_dwordx2 v[14:15], v[2:3], off
	s_nop 0
	v_addc_co_u32_e32 v21, vcc, 0, v3, vcc
	global_load_dwordx2 v[28:29], v[20:21], off offset:3072
	v_add_co_u32_e32 v20, vcc, 0x1000, v2
	global_load_dwordx2 v[16:17], v[16:17], off
	s_nop 0
	v_addc_co_u32_e32 v21, vcc, 0, v3, vcc
	global_load_dwordx2 v[30:31], v[20:21], off offset:1024
	v_add_co_u32_e32 v20, vcc, s93, v2
	s_movk_i32 s8, 0x3000
	s_nop 0
	v_addc_co_u32_e32 v21, vcc, 0, v3, vcc
	global_load_dwordx2 v[32:33], v[20:21], off offset:2048
	v_add_co_u32_e32 v2, vcc, s8, v2
	v_pk_add_f32 v[0:1], v[0:1], v[8:9]
	s_nop 0
	v_addc_co_u32_e32 v3, vcc, 0, v3, vcc
	global_load_dwordx2 v[34:35], v[2:3], off offset:3072
	v_pk_add_f32 v[2:3], v[12:13], v[4:5]
	v_min_u32_e32 v12, 3, v25
	v_pk_add_f32 v[36:37], v[0:1], v[10:11]
	v_add_u32_e32 v0, 1, v12
	v_cvt_f32_ubyte0_e32 v0, v0
	v_add3_u32 v27, 0, v128, v24
	v_min_u32_e32 v24, 2, v25
	v_rcp_iflag_f32_e32 v40, v0
	v_add_u32_e32 v24, 2, v24
	v_cvt_f32_ubyte0_e32 v24, v24
	v_pk_add_f32 v[38:39], v[2:3], v[6:7]
	v_rcp_iflag_f32_e32 v24, v24
	v_pk_add_f32 v[8:9], v[8:9], v[10:11]
	v_pk_add_f32 v[4:5], v[4:5], v[6:7]
	s_mov_b32 s8, 0x3e800000
	s_waitcnt vmcnt(7)
	v_lshlrev_b32_e32 v20, 16, v19
	v_and_b32_e32 v21, 0xffff0000, v19
	s_waitcnt vmcnt(6)
	v_and_b32_e32 v19, 0xffff0000, v22
	s_waitcnt vmcnt(5)
	v_lshlrev_b32_e32 v42, 16, v14
	v_and_b32_e32 v43, 0xffff0000, v14
	v_lshlrev_b32_e32 v44, 16, v15
	v_and_b32_e32 v45, 0xffff0000, v15
	s_waitcnt vmcnt(4)
	v_lshlrev_b32_e32 v0, 16, v28
	v_and_b32_e32 v1, 0xffff0000, v28
	v_lshlrev_b32_e32 v2, 16, v29
	v_and_b32_e32 v3, 0xffff0000, v29
	v_pk_add_f32 v[28:29], v[38:39], v[42:43]
	v_pk_add_f32 v[36:37], v[36:37], v[44:45]
	v_xor_b32_e32 v39, 0x80000000, v45
	v_xor_b32_e32 v38, 0x80000000, v44
	v_xor_b32_e32 v47, 0x80000000, v43
	v_xor_b32_e32 v46, 0x80000000, v42
	s_waitcnt vmcnt(2)
; #define LAS __attribute__((address_space(3)))
; DI unsigned pk2(float a, float b) { f32x2 v = {a, b}; nbf2 r = __builtin_convertvector(v, nbf2); return __builtin_bit_cast(unsigned, r); }
; template <int W>
; DI void pool_fill(LAS bf16_t* dA, const Args& a, int l, int g, int t0, int tid) {
;     ...
;         for (int j = 0; j < 8; ++j) { f32x4 sum = pv[j];
; #pragma unroll
;             for (int i = 1; i < W; ++i) sum += pv[j + i];
;             const int tp = tpos0 + j; const float inv = __builtin_amdgcn_rcpf((float)((tp + 1 < W) ? tp + 1 : W));
;             const f32x4 d = sum * inv - pv[j + W - 1]; u32x2 pw; pw.x = pk2(d[0], d[1]); pw.y = pk2(d[2], d[3]); *(LAS u32x2*)(dA + (lr0 + j) * 136 + c0) = pw; }
	v_lshlrev_b32_e32 v48, 16, v30
	v_and_b32_e32 v49, 0xffff0000, v30
	v_lshlrev_b32_e32 v30, 16, v31
	v_and_b32_e32 v31, 0xffff0000, v31
	v_pk_fma_f32 v[36:37], v[40:41], v[36:37], v[38:39] op_sel_hi:[0,1,1]
	v_pk_fma_f32 v[28:29], v[40:41], v[28:29], v[46:47] op_sel_hi:[0,1,1]
	v_pk_add_f32 v[8:9], v[8:9], v[44:45]
	v_cvt_pk_bf16_f32 v28, v28, v29
	v_cvt_pk_bf16_f32 v29, v36, v37
	v_pk_add_f32 v[4:5], v[4:5], v[42:43]
	v_pk_add_f32 v[8:9], v[8:9], v[30:31]
	v_xor_b32_e32 v37, 0x80000000, v31
	v_xor_b32_e32 v36, 0x80000000, v30
	v_pk_add_f32 v[4:5], v[4:5], v[48:49]
	v_pk_fma_f32 v[8:9], v[24:25], v[8:9], v[36:37] op_sel_hi:[0,1,1]
	v_xor_b32_e32 v37, 0x80000000, v49
	v_xor_b32_e32 v36, 0x80000000, v48
	v_pk_fma_f32 v[4:5], v[24:25], v[4:5], v[36:37] op_sel_hi:[0,1,1]
	v_cvt_pk_bf16_f32 v4, v4, v5
	v_cvt_pk_bf16_f32 v5, v8, v9
	v_rcp_f32_e32 v8, v26
	ds_write2_b64 v27, v[28:29], v[4:5] offset1:34
	v_pk_add_f32 v[4:5], v[6:7], v[42:43]
	v_pk_add_f32 v[6:7], v[10:11], v[44:45]
	s_waitcnt vmcnt(1)
	v_lshlrev_b32_e32 v38, 16, v32
	v_and_b32_e32 v39, 0xffff0000, v32
	v_lshlrev_b32_e32 v32, 16, v33
	v_and_b32_e32 v33, 0xffff0000, v33
	v_pk_add_f32 v[6:7], v[6:7], v[30:31]
	v_pk_add_f32 v[4:5], v[4:5], v[48:49]
	v_pk_add_f32 v[6:7], v[6:7], v[32:33]
	v_xor_b32_e32 v11, 0x80000000, v33
	v_xor_b32_e32 v10, 0x80000000, v32
	v_pk_add_f32 v[4:5], v[4:5], v[38:39]
	v_pk_fma_f32 v[6:7], v[8:9], v[6:7], v[10:11] op_sel_hi:[0,1,1]
	v_xor_b32_e32 v11, 0x80000000, v39
	v_xor_b32_e32 v10, 0x80000000, v38
	v_pk_fma_f32 v[4:5], v[8:9], v[4:5], v[10:11] op_sel_hi:[0,1,1]
	v_pk_add_f32 v[8:9], v[44:45], v[30:31]
	s_waitcnt vmcnt(0)
	v_lshlrev_b32_e32 v50, 16, v34
	v_and_b32_e32 v51, 0xffff0000, v34
	v_lshlrev_b32_e32 v34, 16, v35
	v_and_b32_e32 v35, 0xffff0000, v35
	v_cvt_pk_bf16_f32 v4, v4, v5
	v_cvt_pk_bf16_f32 v5, v6, v7
	v_pk_add_f32 v[6:7], v[42:43], v[48:49]
	v_pk_add_f32 v[8:9], v[8:9], v[32:33]
	v_pk_add_f32 v[6:7], v[6:7], v[38:39]
	v_pk_add_f32 v[8:9], v[8:9], v[34:35]
	v_xor_b32_e32 v11, 0x80000000, v35
	v_xor_b32_e32 v10, 0x80000000, v34
	v_pk_add_f32 v[6:7], v[6:7], v[50:51]
	v_pk_fma_f32 v[8:9], v[8:9], s[8:9], v[10:11] op_sel_hi:[1,0,1]
	v_xor_b32_e32 v11, 0x80000000, v51
	v_xor_b32_e32 v10, 0x80000000, v50
	v_pk_fma_f32 v[6:7], v[6:7], s[8:9], v[10:11] op_sel_hi:[1,0,1]
	v_lshlrev_b32_e32 v14, 16, v17
	v_cvt_pk_bf16_f32 v6, v6, v7
	v_cvt_pk_bf16_f32 v7, v8, v9
	ds_write2_b64 v27, v[4:5], v[6:7] offset0:68 offset1:102
	v_pk_add_f32 v[6:7], v[30:31], v[32:33]
	v_and_b32_e32 v15, 0xffff0000, v17
	v_pk_add_f32 v[4:5], v[48:49], v[38:39]
	v_pk_add_f32 v[6:7], v[6:7], v[34:35]
	v_lshlrev_b32_e32 v12, 16, v16
	v_and_b32_e32 v13, 0xffff0000, v16
	v_pk_add_f32 v[4:5], v[4:5], v[50:51]
	v_pk_add_f32 v[6:7], v[6:7], v[14:15]
	v_xor_b32_e32 v9, 0x80000000, v15
	v_xor_b32_e32 v8, 0x80000000, v14
	v_pk_add_f32 v[4:5], v[4:5], v[12:13]
	v_pk_fma_f32 v[6:7], v[6:7], s[8:9], v[8:9] op_sel_hi:[1,0,1]
	v_xor_b32_e32 v9, 0x80000000, v13
	v_xor_b32_e32 v8, 0x80000000, v12
	v_pk_fma_f32 v[4:5], v[4:5], s[8:9], v[8:9] op_sel_hi:[1,0,1]
	v_pk_add_f32 v[8:9], v[32:33], v[34:35]
	v_cvt_pk_bf16_f32 v4, v4, v5
	v_cvt_pk_bf16_f32 v5, v6, v7
	v_pk_add_f32 v[6:7], v[38:39], v[50:51]
	v_pk_add_f32 v[8:9], v[8:9], v[14:15]
	v_lshlrev_b32_e32 v16, 16, v18
	v_and_b32_e32 v17, 0xffff0000, v18
	v_pk_add_f32 v[6:7], v[6:7], v[12:13]
	v_pk_add_f32 v[8:9], v[8:9], v[20:21]
	v_xor_b32_e32 v11, 0x80000000, v21
	v_xor_b32_e32 v10, 0x80000000, v20
	v_pk_add_f32 v[6:7], v[6:7], v[16:17]
	v_pk_fma_f32 v[8:9], v[8:9], s[8:9], v[10:11] op_sel_hi:[1,0,1]
	v_xor_b32_e32 v11, 0x80000000, v17
	v_xor_b32_e32 v10, 0x80000000, v16
	v_pk_fma_f32 v[6:7], v[6:7], s[8:9], v[10:11] op_sel_hi:[1,0,1]
	v_lshlrev_b32_e32 v18, 16, v22
	v_cvt_pk_bf16_f32 v6, v6, v7
	v_cvt_pk_bf16_f32 v7, v8, v9
	ds_write2_b64 v27, v[4:5], v[6:7] offset0:136 offset1:170
	v_pk_add_f32 v[6:7], v[34:35], v[14:15]
	v_lshlrev_b32_e32 v22, 16, v23
	v_and_b32_e32 v23, 0xffff0000, v23
	v_pk_add_f32 v[4:5], v[50:51], v[12:13]
	v_pk_add_f32 v[6:7], v[6:7], v[20:21]
	v_pk_add_f32 v[4:5], v[4:5], v[16:17]
	v_pk_add_f32 v[6:7], v[6:7], v[22:23]
	v_xor_b32_e32 v9, 0x80000000, v23
	v_xor_b32_e32 v8, 0x80000000, v22
	v_pk_add_f32 v[4:5], v[4:5], v[18:19]
	v_pk_fma_f32 v[6:7], v[6:7], s[8:9], v[8:9] op_sel_hi:[1,0,1]
	v_xor_b32_e32 v9, 0x80000000, v19
	v_xor_b32_e32 v8, 0x80000000, v18
	v_pk_fma_f32 v[4:5], v[4:5], s[8:9], v[8:9] op_sel_hi:[1,0,1]
	s_nop 0
	v_cvt_pk_bf16_f32 v4, v4, v5
	v_cvt_pk_bf16_f32 v5, v6, v7
	ds_write_b64 v27, v[4:5] offset:1632
	v_pk_add_f32 v[4:5], v[14:15], v[20:21]
	v_pk_add_f32 v[6:7], v[12:13], v[16:17]
	v_pk_add_f32 v[4:5], v[4:5], v[22:23]
	v_pk_add_f32 v[8:9], v[6:7], v[18:19]
	v_pk_add_f32 v[6:7], v[4:5], v[2:3]
	v_pk_add_f32 v[4:5], v[8:9], v[0:1]
